# speedup vs baseline: 1.0200x; 1.0003x over previous
; #define SLOAD(i, k0) do { sr_[i].vs0 = *reinterpret_cast<const bf16x8*>(&Vh[(size_t)((k0) + sr) * LDQ + sc]); sr_[i].vs1 = *reinterpret_cast<const bf16x8*>(&Vh[(size_t)((k0) + 32 + sr) * LDQ + sc]); \
;     sr_[i].ks0 = *reinterpret_cast<const bf16x8*>(&Kh[(size_t)((k0) + sr) * LDQ + sc]); sr_[i].ks1 = *reinterpret_cast<const bf16x8*>(&Kh[(size_t)((k0) + 32 + sr) * LDQ + sc]); } while (0)
; #define SWRITE(b, i) do { *(bf16x8*)((char*)V_lds + (b) * SHM_V + vst0) = sr_[i].vs0;          \
;     *(bf16x8*)((char*)V_lds + (b) * SHM_V + vst1) = sr_[i].vs1; int kc = sc * 2;               \
;     *(bf16x8*)((char*)K_lds + (b) * SHM_K + KSWZ(sr, kc)) = sr_[i].ks0;                       \
;     *(bf16x8*)((char*)K_lds + (b) * SHM_K + KSWZ(32 + sr, kc)) = sr_[i].ks1; } while (0)
; template <bool SAFE>
; __device__ __forceinline__ void diff_core(const bf16* __restrict__ Kh, const bf16* __restrict__ Vh, const int NT, const bf16x8* qr, char* lds,
;                                           const int wid, const int lane_unused, f32x16* o, f32x16& lacc, float& l_reg) {
;     ...
;   const int kw0 = KSWZ(sr, sc * 2), kw1 = KSWZ(32 + sr, sc * 2);
;   SLOAD(0, 0); asm volatile("s_waitcnt vmcnt(0)" ::: "memory"); SWRITE(0, 0);
;   SLOAD(0, 64); asm volatile("s_waitcnt vmcnt(0)" ::: "memory"); SWRITE(1, 0); __syncthreads();
;   SLOAD(0, 128);
;   FIXUP(K_lds, true);
;   int bc = 1, bp = 0, bn = 2;
.LBB0_104:
	s_or_b64 exec, exec, s[4:5]
	v_and_b32_e32 v200, 63, v0
	v_lshlrev_b32_e32 v0, 4, v2
	v_and_b32_e32 v0, 0xc0, v0
	v_and_or_b32 v0, v1, 24, v0
	v_and_b32_e32 v2, 32, v4
	v_and_b32_e32 v1, 0x100, v1
	s_waitcnt lgkmcnt(0)
	v_add_u32_e32 v9, s62, v3
	v_or3_b32 v8, v0, v2, v1
	ds_read_b128 v[0:3], v9 offset:192
	ds_read_b128 v[4:7], v9 offset:224
	ds_read_b128 v[50:53], v9 offset:128
	ds_read_b128 v[54:57], v9 offset:160
	v_sub_f32_e32 v16, v16, v48
	v_sub_f32_e32 v17, v17, v48
	v_sub_f32_e32 v18, v18, v48
	v_sub_f32_e32 v19, v19, v48
	v_sub_f32_e32 v20, v20, v48
	v_sub_f32_e32 v21, v21, v48
	v_sub_f32_e32 v22, v22, v48
	v_sub_f32_e32 v23, v23, v48
	v_sub_f32_e32 v24, v24, v48
	v_sub_f32_e32 v25, v25, v48
	v_sub_f32_e32 v26, v26, v48
	v_sub_f32_e32 v27, v27, v48
	v_sub_f32_e32 v28, v28, v48
	v_sub_f32_e32 v29, v29, v48
	v_sub_f32_e32 v30, v30, v48
	v_sub_f32_e32 v31, v31, v48
	v_sub_f32_e32 v32, v32, v48
	v_sub_f32_e32 v33, v33, v48
	v_sub_f32_e32 v34, v34, v48
	v_sub_f32_e32 v35, v35, v48
	v_sub_f32_e32 v36, v36, v48
	v_sub_f32_e32 v37, v37, v48
	v_sub_f32_e32 v38, v38, v48
	v_sub_f32_e32 v39, v39, v48
	v_sub_f32_e32 v40, v40, v48
	v_sub_f32_e32 v41, v41, v48
	v_sub_f32_e32 v42, v42, v48
	v_sub_f32_e32 v43, v43, v48
	v_sub_f32_e32 v44, v44, v48
	v_sub_f32_e32 v45, v45, v48
	v_sub_f32_e32 v46, v46, v48
	v_sub_f32_e32 v47, v47, v48
	v_exp_f32_e32 v16, v16
	v_exp_f32_e32 v17, v17
	v_exp_f32_e32 v18, v18
	v_exp_f32_e32 v19, v19
	v_exp_f32_e32 v20, v20
	v_exp_f32_e32 v21, v21
	v_exp_f32_e32 v22, v22
	v_exp_f32_e32 v23, v23
	v_exp_f32_e32 v24, v24
	v_exp_f32_e32 v25, v25
	v_exp_f32_e32 v26, v26
	v_exp_f32_e32 v27, v27
	v_exp_f32_e32 v28, v28
	v_exp_f32_e32 v29, v29
	v_exp_f32_e32 v30, v30
	v_exp_f32_e32 v31, v31
	v_exp_f32_e32 v32, v32
	v_exp_f32_e32 v33, v33
	v_exp_f32_e32 v34, v34
	v_exp_f32_e32 v35, v35
	v_exp_f32_e32 v36, v36
	v_exp_f32_e32 v37, v37
	v_exp_f32_e32 v38, v38
	v_exp_f32_e32 v39, v39
	v_exp_f32_e32 v40, v40
	v_exp_f32_e32 v41, v41
	v_exp_f32_e32 v42, v42
	v_exp_f32_e32 v43, v43
	v_exp_f32_e32 v44, v44
	v_exp_f32_e32 v45, v45
	v_exp_f32_e32 v46, v46
	v_exp_f32_e32 v47, v47
	s_lshl_b32 s12, s8, 7
	s_cmp_lg_u32 0, -1
	s_cselect_b32 s5, 0, 0
	s_waitcnt lgkmcnt(2)
	v_pk_mul_f32 v[14:15], v[6:7], 0 op_sel_hi:[1,0]
	v_xor_b32_e32 v80, 0x80000000, v48
	v_add_u32_e32 v211, s5, v8
	v_pk_mul_f32 v[10:11], v[2:3], 0 op_sel_hi:[1,0]
	s_waitcnt lgkmcnt(0)
	v_pk_mul_f32 v[6:7], v[56:57], 0 op_sel_hi:[1,0]
	v_pk_mul_f32 v[2:3], v[52:53], 0 op_sel_hi:[1,0]
	v_pk_mul_f32 v[12:13], v[4:5], 0 op_sel_hi:[1,0]
	v_pk_mul_f32 v[8:9], v[0:1], 0 op_sel_hi:[1,0]
	v_pk_mul_f32 v[4:5], v[54:55], 0 op_sel_hi:[1,0]
	v_pk_mul_f32 v[0:1], v[50:51], 0 op_sel_hi:[1,0]
	v_cvt_pk_bf16_f32 v160, v16, v17
	v_cvt_pk_bf16_f32 v161, v18, v19
	v_cvt_pk_bf16_f32 v182, v20, v21
	v_cvt_pk_bf16_f32 v183, v22, v23
	v_cvt_pk_bf16_f32 v170, v24, v25
	v_cvt_pk_bf16_f32 v171, v26, v27
	v_cvt_pk_bf16_f32 v186, v28, v29
	v_cvt_pk_bf16_f32 v187, v30, v31
	v_cvt_pk_bf16_f32 v180, v32, v33
	v_cvt_pk_bf16_f32 v181, v34, v35
	v_cvt_pk_bf16_f32 v178, v36, v37
	v_cvt_pk_bf16_f32 v179, v38, v39
	v_cvt_pk_bf16_f32 v188, v40, v41
	v_cvt_pk_bf16_f32 v189, v42, v43
	v_cvt_pk_bf16_f32 v174, v44, v45
	v_cvt_pk_bf16_f32 v175, v46, v47
	v_mov_b32_e32 v64, 0
	v_mov_b64_e32 v[46:47], v[14:15]
	v_mov_b64_e32 v[62:63], v[14:15]
	v_mov_b64_e32 v[30:31], v[14:15]
	v_mov_b32_e32 v81, v80
	v_mov_b32_e32 v82, v80
	v_mov_b32_e32 v83, v80
	v_mov_b32_e32 v84, v80
	v_mov_b32_e32 v85, v80
	v_mov_b32_e32 v86, v80
	v_mov_b32_e32 v87, v80
	v_mov_b32_e32 v88, v80
	v_mov_b32_e32 v89, v80
	v_mov_b32_e32 v90, v80
	v_mov_b32_e32 v91, v80
	v_mov_b32_e32 v92, v80
	v_mov_b32_e32 v93, v80
	v_mov_b32_e32 v94, v80
	v_mov_b32_e32 v95, v80
	s_mov_b32 s4, 0
	s_mov_b32 s5, 1
	v_lshl_add_u64 v[190:191], s[10:11], 0, v[194:195]
	v_mad_u32_u24 v247, v201, s80, v194
	s_add_i32 s93, s92, -1
	s_mov_b32 s9, 2
	v_mov_b64_e32 v[44:45], v[12:13]
	v_mov_b64_e32 v[42:43], v[10:11]
	v_mov_b64_e32 v[40:41], v[8:9]
	v_mov_b64_e32 v[38:39], v[6:7]
	v_mov_b64_e32 v[36:37], v[4:5]
	v_mov_b64_e32 v[34:35], v[2:3]
	v_mov_b64_e32 v[32:33], v[0:1]
	v_mov_b64_e32 v[60:61], v[12:13]
	v_mov_b64_e32 v[58:59], v[10:11]
	v_mov_b64_e32 v[56:57], v[8:9]
	v_mov_b64_e32 v[54:55], v[6:7]
	v_mov_b64_e32 v[52:53], v[4:5]
	v_mov_b64_e32 v[50:51], v[2:3]
	v_mov_b64_e32 v[48:49], v[0:1]
	v_mov_b64_e32 v[28:29], v[12:13]
	v_mov_b64_e32 v[26:27], v[10:11]
	v_mov_b64_e32 v[24:25], v[8:9]
	v_mov_b64_e32 v[22:23], v[6:7]
	v_mov_b64_e32 v[20:21], v[4:5]
	v_mov_b64_e32 v[18:19], v[2:3]
	v_mov_b64_e32 v[16:17], v[0:1]
	s_mov_b32 s6, 1
	v_mov_b32_e32 v65, v64
	v_mov_b32_e32 v66, v64
	v_mov_b32_e32 v67, v64
	v_mov_b32_e32 v68, v64
	v_mov_b32_e32 v69, v64
	v_mov_b32_e32 v70, v64
	v_mov_b32_e32 v71, v64
	v_mov_b32_e32 v72, v64
	v_mov_b32_e32 v73, v64
	v_mov_b32_e32 v74, v64
	v_mov_b32_e32 v75, v64
	v_mov_b32_e32 v76, v64
	v_mov_b32_e32 v77, v64
	v_mov_b32_e32 v78, v64
	v_mov_b32_e32 v79, v64
	v_mov_b32_e32 v176, v180
	v_mov_b32_e32 v177, v181
	v_mov_b32_e32 v180, v160
	v_mov_b32_e32 v181, v161
	v_mov_b32_e32 v184, v170
	v_mov_b32_e32 v185, v171
	v_mov_b32_e32 v172, v188
	v_mov_b32_e32 v173, v189
	v_add_u32_e32 v76, 0xc000, v207
	v_add_u32_e32 v77, 0xc000, v208
	v_add_u32_e32 v78, 0xc000, v209
	v_add_u32_e32 v79, 0xc000, v210
	v_add_u32_e32 v188, 0xc000, v203
	v_add_u32_e32 v189, 0xc000, v204
	ds_read_b128 v[68:71], v76 offset:16384
	ds_read_b128 v[72:75], v76 offset:24576
	s_waitcnt lgkmcnt(0)
; #define SBAR() __builtin_amdgcn_sched_barrier(0)
; template <bool SAFE> ...
;   bf16x8 kb[8];
; #pragma unroll
;   for (int d0 = 0; d0 < 4; ++d0) { const int cb = (cb0 + d0 * 16 + hi * 8) * 2;
;     kb[2 * d0] = *reinterpret_cast<const bf16x8*>((const char*)Ks + KSWZ(r32, cb));
;     kb[2 * d0 + 1] = *reinterpret_cast<const bf16x8*>((const char*)Ks + KSWZ(32 + r32, cb)); }
;   VFrag fa, fb;
;   vfrag_issue<0>(fa, vb);
;   p0 = MFMA32(kb[0], qr[0], cinit); p1 = MFMA32(kb[1], qr[0], cinit);
; #pragma unroll
;   for (int d0 = 1; d0 < 4; ++d0) { p0 = MFMA32(kb[2 * d0], qr[d0], p0); p1 = MFMA32(kb[2 * d0 + 1], qr[d0], p1); }
;   SBAR();
;   unsigned a0, a1, b0, b1; ps = 0.f;
;   fused_ks<0, SAFE>(o, lacc, vb, fa, fb, p0, p1, ps, a0, a1, b0, b1, pa0, pa1, pa2, pa3, st, sd, dow, ones);
;   fused_ks<1, SAFE>(o, lacc, vb, fb, fa, p0, p1, ps, a0, a1, b0, b1, pa0, pa1, pa2, pa3, st, sd, dow, ones);
;   fused_ks<2, SAFE>(o, lacc, vb, fa, fb, p0, p1, ps, a0, a1, b0, b1, pa0, pa1, pa2, pa3, st, sd, dow, ones);
;   fused_ks<3, SAFE>(o, lacc, vb, fb, fa, p0, p1, ps, a0, a1, b0, b1, pa0, pa1, pa2, pa3, st, sd, dow, ones);
;   SM2_UNIT(7);
;   if constexpr (SAFE) { auto rr = __builtin_amdgcn_permlane32_swap(__float_as_uint(ps), __float_as_uint(ps), false, false);
;     ps = __uint_as_float(rr[0]) + __uint_as_float(rr[1]); }
;   SBAR();
; }
; template <bool SAFE>
; __device__ __forceinline__ void diff_core(const bf16* __restrict__ Kh, const bf16* __restrict__ Vh, const int NT, const bf16x8* qr, char* lds,
;                                           const int wid, const int lane_unused, f32x16* o, f32x16& lacc, float& l_reg) {
;     ...
;   for (int j = 1; j < NT; ++j) {
;     const bool dow = true;
;     const bf16* Kc = (const bf16*)((const char*)K_lds + bc * SHM_K);
;     StgDst sd;
;     sd.v0 = (char*)V_lds + bn * SHM_V + vst0; sd.v1 = (char*)V_lds + bn * SHM_V + vst1;
;     sd.k0 = (char*)K_lds + bn * SHM_K + kw0;  sd.k1 = (char*)K_lds + bn * SHM_K + kw1;
;     tile_step<SAFE>(o, lacc, Kc, vb0 + bp * SHM_V, qr, rk, hi, cb0, p0, p1, cinit, ps, pa0, pa1, pa2, pa3, sr_[0], sd, dow, ones);
;     SLOAD(0, min(j + 2, NT - 1) * 64);
;     SBAR();
;     if constexpr (SAFE) FIXUP(Kc, false);
;     asm volatile("s_waitcnt lgkmcnt(0)" ::: "memory"); __builtin_amdgcn_s_barrier(); asm volatile("" ::: "memory");
;     const int t_ = bp; bp = bc; bc = bn; bn = t_;
.LBB0_105:
	ds_read_b128 v[212:215], v77 offset:16384
	ds_read_b128 v[216:219], v77 offset:24576
	s_add_i32 s98, s5, 2
	s_min_i32 s98, s98, s93
	s_mul_i32 s98, s98, 0x60000
	s_add_u32 s98, s10, s98
	s_addc_u32 s99, s11, 0
	s_add_u32 s100, s98, 0x30000
	s_addc_u32 s101, s99, 0
	v_mfma_f32_32x32x16_bf16 v[112:127], v[68:71], v[132:135], v[80:95]
	v_mfma_f32_32x32x16_bf16 v[96:111], v[72:75], v[132:135], v[80:95]
	ds_read_b128 v[68:71], v78 offset:16384
	ds_read_b128 v[72:75], v78 offset:24576
	v_mfma_f32_16x16x32_bf16 v[64:67], v[180:183], v[148:151], v[64:67]
	s_waitcnt lgkmcnt(3)
	v_mfma_f32_32x32x16_bf16 v[112:127], v[212:215], v[136:139], v[112:127]
	ds_read_b128 v[212:215], v79 offset:16384
	s_waitcnt vmcnt(3)
	ds_write_b128 v188, v[166:169] offset:32768
	global_load_dwordx4 v[166:169], v247, s[98:99] offset:1024
	s_waitcnt lgkmcnt(4)
	v_mfma_f32_32x32x16_bf16 v[96:111], v[216:219], v[136:139], v[96:111]
	ds_read_b128 v[216:219], v79 offset:24576
	v_mfma_f32_16x16x32_bf16 v[64:67], v[184:187], v[148:151], v[64:67]
	s_waitcnt lgkmcnt(4)
	v_mfma_f32_32x32x16_bf16 v[112:127], v[68:71], v[140:143], v[112:127]
	ds_read_b64_tr_b16 v[220:221], v211 offset:0
	ds_read_b64_tr_b16 v[222:223], v211 offset:2048
	s_waitcnt vmcnt(3)
	ds_write_b128 v189, v[162:165] offset:32768
	global_load_dwordx4 v[162:165], v247, s[100:101] offset:1024
	v_mfma_f32_16x16x32_bf16 v[64:67], v[176:179], v[148:151], v[64:67]
	s_waitcnt lgkmcnt(6)
	v_mfma_f32_32x32x16_bf16 v[96:111], v[72:75], v[140:143], v[96:111]
	v_mfma_f32_16x16x32_bf16 v[64:67], v[172:175], v[148:151], v[64:67]
	s_waitcnt lgkmcnt(5)
	v_mfma_f32_32x32x16_bf16 v[112:127], v[212:215], v[144:147], v[112:127]
	ds_read_b64_tr_b16 v[212:213], v211 offset:512
	ds_read_b64_tr_b16 v[214:215], v211 offset:2560
	ds_read_b64_tr_b16 v[224:225], v211 offset:1024
	ds_read_b64_tr_b16 v[226:227], v211 offset:3072
	ds_read_b64_tr_b16 v[228:229], v211 offset:1536
	ds_read_b64_tr_b16 v[230:231], v211 offset:3584
	s_waitcnt lgkmcnt(7)
	v_mfma_f32_32x32x16_bf16 v[96:111], v[216:219], v[144:147], v[96:111]
	ds_read_b64_tr_b16 v[216:217], v211 offset:4096
	ds_read_b64_tr_b16 v[218:219], v211 offset:6144
	ds_read_b64_tr_b16 v[232:233], v211 offset:4608
	ds_read_b64_tr_b16 v[234:235], v211 offset:6656
	ds_read_b64_tr_b16 v[236:237], v211 offset:5120
	ds_read_b64_tr_b16 v[238:239], v211 offset:7168
	ds_read_b64_tr_b16 v[240:241], v211 offset:5632
	ds_read_b64_tr_b16 v[242:243], v211 offset:7680
	s_waitcnt lgkmcnt(8)
	v_mfma_f32_32x32x16_bf16 v[48:63], v[180:183], v[220:223], v[48:63]
	s_nop 0
	v_exp_f32_e32 v112, v112
	v_exp_f32_e32 v113, v113
	v_mfma_f32_32x32x16_bf16 v[32:47], v[180:183], v[212:215], v[32:47]
	v_exp_f32_e32 v114, v114
	v_exp_f32_e32 v115, v115
	v_mfma_f32_32x32x16_bf16 v[0:15], v[180:183], v[224:227], v[0:15]
	v_exp_f32_e32 v171, v116
	v_exp_f32_e32 v220, v117
	v_mfma_f32_32x32x16_bf16 v[16:31], v[180:183], v[228:231], v[16:31]
	v_exp_f32_e32 v221, v118
	v_exp_f32_e32 v222, v119
	v_cvt_pk_bf16_f32 v180, v112, v113
	v_cvt_pk_bf16_f32 v181, v114, v115
	ds_read_b64_tr_b16 v[112:113], v211 offset:8192
	ds_read_b64_tr_b16 v[114:115], v211 offset:10240
	ds_read_b64_tr_b16 v[116:117], v211 offset:8704
	ds_read_b64_tr_b16 v[118:119], v211 offset:10752
	ds_read_b64_tr_b16 v[248:249], v211 offset:9216
	ds_read_b64_tr_b16 v[250:251], v211 offset:11264
	ds_read_b64_tr_b16 v[212:213], v211 offset:9728
	ds_read_b64_tr_b16 v[214:215], v211 offset:11776
	s_waitcnt lgkmcnt(8)
	v_mfma_f32_32x32x16_bf16 v[48:63], v[184:187], v[216:219], v[48:63]
	v_cvt_pk_bf16_f32 v182, v171, v220
	v_cvt_pk_bf16_f32 v183, v221, v222
	v_exp_f32_e32 v120, v120
	v_exp_f32_e32 v121, v121
	v_mfma_f32_32x32x16_bf16 v[32:47], v[184:187], v[232:235], v[32:47]
	v_exp_f32_e32 v122, v122
	v_exp_f32_e32 v123, v123
	v_mfma_f32_32x32x16_bf16 v[0:15], v[184:187], v[236:239], v[0:15]
	v_exp_f32_e32 v160, v124
	v_exp_f32_e32 v161, v125
	v_mfma_f32_32x32x16_bf16 v[16:31], v[184:187], v[240:243], v[16:31]
	v_exp_f32_e32 v220, v126
	v_exp_f32_e32 v221, v127
	v_cvt_pk_bf16_f32 v184, v120, v121
	v_cvt_pk_bf16_f32 v185, v122, v123
	s_waitcnt lgkmcnt(0)
	s_barrier
	v_mfma_f32_32x32x16_bf16 v[48:63], v[176:179], v[112:115], v[48:63]
	ds_read_b128 v[68:71], v76 offset:32768
	ds_read_b128 v[72:75], v76 offset:40960
	ds_read_b64_tr_b16 v[120:121], v211 offset:12288
	ds_read_b64_tr_b16 v[122:123], v211 offset:14336
	ds_read_b64_tr_b16 v[124:125], v211 offset:12800
	ds_read_b64_tr_b16 v[126:127], v211 offset:14848
	ds_read_b64_tr_b16 v[252:253], v211 offset:13312
	ds_read_b64_tr_b16 v[254:255], v211 offset:15360
	ds_read_b64_tr_b16 v[216:217], v211 offset:13824
	ds_read_b64_tr_b16 v[218:219], v211 offset:15872
	v_cvt_pk_bf16_f32 v186, v160, v161
	v_cvt_pk_bf16_f32 v187, v220, v221
	v_exp_f32_e32 v96, v96
	v_exp_f32_e32 v97, v97
	v_mfma_f32_32x32x16_bf16 v[32:47], v[176:179], v[116:119], v[32:47]
	v_exp_f32_e32 v98, v98
	v_exp_f32_e32 v99, v99
	s_waitcnt vmcnt(3)
	ds_write_b128 v205, v[156:159] offset:32768
	global_load_dwordx4 v[156:159], v247, s[98:99] offset:2048
	v_mfma_f32_32x32x16_bf16 v[0:15], v[176:179], v[248:251], v[0:15]
	v_exp_f32_e32 v100, v100
	v_exp_f32_e32 v101, v101
	v_mfma_f32_32x32x16_bf16 v[16:31], v[176:179], v[212:215], v[16:31]
	v_cvt_pk_bf16_f32 v176, v96, v97
	v_cvt_pk_bf16_f32 v177, v98, v99
	v_exp_f32_e32 v96, v102
	v_exp_f32_e32 v97, v103
	s_waitcnt lgkmcnt(0)
	v_mfma_f32_32x32x16_bf16 v[48:63], v[172:175], v[120:123], v[48:63]
	v_cvt_pk_bf16_f32 v178, v100, v101
	v_cvt_pk_bf16_f32 v179, v96, v97
	v_exp_f32_e32 v98, v104
	v_exp_f32_e32 v99, v105
	v_mfma_f32_32x32x16_bf16 v[32:47], v[172:175], v[124:127], v[32:47]
	v_exp_f32_e32 v96, v106
	v_exp_f32_e32 v97, v107
	s_waitcnt vmcnt(3)
	ds_write_b128 v206, v[152:155] offset:32768
	global_load_dwordx4 v[152:155], v247, s[100:101] offset:2048
	v_mfma_f32_32x32x16_bf16 v[0:15], v[172:175], v[252:255], v[0:15]
	v_exp_f32_e32 v100, v108
	v_exp_f32_e32 v101, v109
	v_mfma_f32_32x32x16_bf16 v[16:31], v[172:175], v[216:219], v[16:31]
	v_cvt_pk_bf16_f32 v172, v98, v99
	v_cvt_pk_bf16_f32 v173, v96, v97
	v_exp_f32_e32 v102, v110
	v_exp_f32_e32 v103, v111
	v_cvt_pk_bf16_f32 v174, v100, v101
	v_cvt_pk_bf16_f32 v175, v102, v103
	s_add_i32 s5, s5, 1
	s_cmp_lg_u32 s92, s5
	s_cbranch_scc0 .Lunr0_x0
; #define SBAR() __builtin_amdgcn_sched_barrier(0)
; template <bool SAFE> ...
;   bf16x8 kb[8];
; #pragma unroll
;   for (int d0 = 0; d0 < 4; ++d0) { const int cb = (cb0 + d0 * 16 + hi * 8) * 2;
;     kb[2 * d0] = *reinterpret_cast<const bf16x8*>((const char*)Ks + KSWZ(r32, cb));
;     kb[2 * d0 + 1] = *reinterpret_cast<const bf16x8*>((const char*)Ks + KSWZ(32 + r32, cb)); }
;   VFrag fa, fb;
;   vfrag_issue<0>(fa, vb);
;   p0 = MFMA32(kb[0], qr[0], cinit); p1 = MFMA32(kb[1], qr[0], cinit);
; #pragma unroll
;   for (int d0 = 1; d0 < 4; ++d0) { p0 = MFMA32(kb[2 * d0], qr[d0], p0); p1 = MFMA32(kb[2 * d0 + 1], qr[d0], p1); }
;   SBAR();
;   unsigned a0, a1, b0, b1; ps = 0.f;
;   fused_ks<0, SAFE>(o, lacc, vb, fa, fb, p0, p1, ps, a0, a1, b0, b1, pa0, pa1, pa2, pa3, st, sd, dow, ones);
;   fused_ks<1, SAFE>(o, lacc, vb, fb, fa, p0, p1, ps, a0, a1, b0, b1, pa0, pa1, pa2, pa3, st, sd, dow, ones);
;   fused_ks<2, SAFE>(o, lacc, vb, fa, fb, p0, p1, ps, a0, a1, b0, b1, pa0, pa1, pa2, pa3, st, sd, dow, ones);
;   fused_ks<3, SAFE>(o, lacc, vb, fb, fa, p0, p1, ps, a0, a1, b0, b1, pa0, pa1, pa2, pa3, st, sd, dow, ones);
;   SM2_UNIT(7);
;   if constexpr (SAFE) { auto rr = __builtin_amdgcn_permlane32_swap(__float_as_uint(ps), __float_as_uint(ps), false, false);
;     ps = __uint_as_float(rr[0]) + __uint_as_float(rr[1]); }
;   SBAR();
; }
; template <bool SAFE>
; __device__ __forceinline__ void diff_core(const bf16* __restrict__ Kh, const bf16* __restrict__ Vh, const int NT, const bf16x8* qr, char* lds,
;                                           const int wid, const int lane_unused, f32x16* o, f32x16& lacc, float& l_reg) {
;     ...
;   for (int j = 1; j < NT; ++j) {
;     const bool dow = true;
;     const bf16* Kc = (const bf16*)((const char*)K_lds + bc * SHM_K);
;     StgDst sd;
;     sd.v0 = (char*)V_lds + bn * SHM_V + vst0; sd.v1 = (char*)V_lds + bn * SHM_V + vst1;
;     sd.k0 = (char*)K_lds + bn * SHM_K + kw0;  sd.k1 = (char*)K_lds + bn * SHM_K + kw1;
;     tile_step<SAFE>(o, lacc, Kc, vb0 + bp * SHM_V, qr, rk, hi, cb0, p0, p1, cinit, ps, pa0, pa1, pa2, pa3, sr_[0], sd, dow, ones);
;     SLOAD(0, min(j + 2, NT - 1) * 64);
;     SBAR();
;     if constexpr (SAFE) FIXUP(Kc, false);
;     asm volatile("s_waitcnt lgkmcnt(0)" ::: "memory"); __builtin_amdgcn_s_barrier(); asm volatile("" ::: "memory");
;     const int t_ = bp; bp = bc; bc = bn; bn = t_;
	ds_read_b128 v[212:215], v77 offset:32768
	ds_read_b128 v[216:219], v77 offset:40960
	s_add_i32 s98, s5, 2
	s_min_i32 s98, s98, s93
	s_mul_i32 s98, s98, 0x60000
	s_add_u32 s98, s10, s98
	s_addc_u32 s99, s11, 0
	s_add_u32 s100, s98, 0x30000
	s_addc_u32 s101, s99, 0
	v_mfma_f32_32x32x16_bf16 v[112:127], v[68:71], v[132:135], v[80:95]
	v_mfma_f32_32x32x16_bf16 v[96:111], v[72:75], v[132:135], v[80:95]
	ds_read_b128 v[68:71], v78 offset:32768
	ds_read_b128 v[72:75], v78 offset:40960
	v_mfma_f32_16x16x32_bf16 v[64:67], v[180:183], v[148:151], v[64:67]
	s_waitcnt lgkmcnt(3)
	v_mfma_f32_32x32x16_bf16 v[112:127], v[212:215], v[136:139], v[112:127]
	ds_read_b128 v[212:215], v79 offset:32768
	s_waitcnt vmcnt(3)
	ds_write_b128 v188, v[166:169] offset:0
	global_load_dwordx4 v[166:169], v247, s[98:99] offset:1024
	s_waitcnt lgkmcnt(4)
	v_mfma_f32_32x32x16_bf16 v[96:111], v[216:219], v[136:139], v[96:111]
	ds_read_b128 v[216:219], v79 offset:40960
	v_mfma_f32_16x16x32_bf16 v[64:67], v[184:187], v[148:151], v[64:67]
	s_waitcnt lgkmcnt(4)
	v_mfma_f32_32x32x16_bf16 v[112:127], v[68:71], v[140:143], v[112:127]
	ds_read_b64_tr_b16 v[220:221], v211 offset:16384
	ds_read_b64_tr_b16 v[222:223], v211 offset:18432
	s_waitcnt vmcnt(3)
	ds_write_b128 v189, v[162:165] offset:0
	global_load_dwordx4 v[162:165], v247, s[100:101] offset:1024
	v_mfma_f32_16x16x32_bf16 v[64:67], v[176:179], v[148:151], v[64:67]
	s_waitcnt lgkmcnt(6)
	v_mfma_f32_32x32x16_bf16 v[96:111], v[72:75], v[140:143], v[96:111]
	v_mfma_f32_16x16x32_bf16 v[64:67], v[172:175], v[148:151], v[64:67]
	s_waitcnt lgkmcnt(5)
	v_mfma_f32_32x32x16_bf16 v[112:127], v[212:215], v[144:147], v[112:127]
	ds_read_b64_tr_b16 v[212:213], v211 offset:16896
	ds_read_b64_tr_b16 v[214:215], v211 offset:18944
	ds_read_b64_tr_b16 v[224:225], v211 offset:17408
	ds_read_b64_tr_b16 v[226:227], v211 offset:19456
	ds_read_b64_tr_b16 v[228:229], v211 offset:17920
	ds_read_b64_tr_b16 v[230:231], v211 offset:19968
	s_waitcnt lgkmcnt(7)
	v_mfma_f32_32x32x16_bf16 v[96:111], v[216:219], v[144:147], v[96:111]
	ds_read_b64_tr_b16 v[216:217], v211 offset:20480
	ds_read_b64_tr_b16 v[218:219], v211 offset:22528
	ds_read_b64_tr_b16 v[232:233], v211 offset:20992
	ds_read_b64_tr_b16 v[234:235], v211 offset:23040
	ds_read_b64_tr_b16 v[236:237], v211 offset:21504
	ds_read_b64_tr_b16 v[238:239], v211 offset:23552
	ds_read_b64_tr_b16 v[240:241], v211 offset:22016
	ds_read_b64_tr_b16 v[242:243], v211 offset:24064
	s_waitcnt lgkmcnt(8)
	v_mfma_f32_32x32x16_bf16 v[48:63], v[180:183], v[220:223], v[48:63]
	s_nop 0
	v_exp_f32_e32 v112, v112
	v_exp_f32_e32 v113, v113
	v_mfma_f32_32x32x16_bf16 v[32:47], v[180:183], v[212:215], v[32:47]
	v_exp_f32_e32 v114, v114
	v_exp_f32_e32 v115, v115
	v_mfma_f32_32x32x16_bf16 v[0:15], v[180:183], v[224:227], v[0:15]
	v_exp_f32_e32 v171, v116
	v_exp_f32_e32 v220, v117
	v_mfma_f32_32x32x16_bf16 v[16:31], v[180:183], v[228:231], v[16:31]
	v_exp_f32_e32 v221, v118
	v_exp_f32_e32 v222, v119
	v_cvt_pk_bf16_f32 v180, v112, v113
	v_cvt_pk_bf16_f32 v181, v114, v115
	ds_read_b64_tr_b16 v[112:113], v211 offset:24576
	ds_read_b64_tr_b16 v[114:115], v211 offset:26624
	ds_read_b64_tr_b16 v[116:117], v211 offset:25088
	ds_read_b64_tr_b16 v[118:119], v211 offset:27136
	ds_read_b64_tr_b16 v[248:249], v211 offset:25600
	ds_read_b64_tr_b16 v[250:251], v211 offset:27648
	ds_read_b64_tr_b16 v[212:213], v211 offset:26112
	ds_read_b64_tr_b16 v[214:215], v211 offset:28160
	s_waitcnt lgkmcnt(8)
	v_mfma_f32_32x32x16_bf16 v[48:63], v[184:187], v[216:219], v[48:63]
	v_cvt_pk_bf16_f32 v182, v171, v220
	v_cvt_pk_bf16_f32 v183, v221, v222
	v_exp_f32_e32 v120, v120
	v_exp_f32_e32 v121, v121
	v_mfma_f32_32x32x16_bf16 v[32:47], v[184:187], v[232:235], v[32:47]
	v_exp_f32_e32 v122, v122
	v_exp_f32_e32 v123, v123
	v_mfma_f32_32x32x16_bf16 v[0:15], v[184:187], v[236:239], v[0:15]
	v_exp_f32_e32 v160, v124
	v_exp_f32_e32 v161, v125
	v_mfma_f32_32x32x16_bf16 v[16:31], v[184:187], v[240:243], v[16:31]
	v_exp_f32_e32 v220, v126
	v_exp_f32_e32 v221, v127
	v_cvt_pk_bf16_f32 v184, v120, v121
	v_cvt_pk_bf16_f32 v185, v122, v123
	s_waitcnt lgkmcnt(0)
	s_barrier
	v_mfma_f32_32x32x16_bf16 v[48:63], v[176:179], v[112:115], v[48:63]
	ds_read_b128 v[68:71], v76 offset:0
	ds_read_b128 v[72:75], v76 offset:8192
	ds_read_b64_tr_b16 v[120:121], v211 offset:28672
	ds_read_b64_tr_b16 v[122:123], v211 offset:30720
	ds_read_b64_tr_b16 v[124:125], v211 offset:29184
	ds_read_b64_tr_b16 v[126:127], v211 offset:31232
	ds_read_b64_tr_b16 v[252:253], v211 offset:29696
	ds_read_b64_tr_b16 v[254:255], v211 offset:31744
	ds_read_b64_tr_b16 v[216:217], v211 offset:30208
	ds_read_b64_tr_b16 v[218:219], v211 offset:32256
	v_cvt_pk_bf16_f32 v186, v160, v161
	v_cvt_pk_bf16_f32 v187, v220, v221
	v_exp_f32_e32 v96, v96
	v_exp_f32_e32 v97, v97
	v_mfma_f32_32x32x16_bf16 v[32:47], v[176:179], v[116:119], v[32:47]
	v_exp_f32_e32 v98, v98
	v_exp_f32_e32 v99, v99
	s_waitcnt vmcnt(3)
	ds_write_b128 v205, v[156:159] offset:0
	global_load_dwordx4 v[156:159], v247, s[98:99] offset:2048
	v_mfma_f32_32x32x16_bf16 v[0:15], v[176:179], v[248:251], v[0:15]
	v_exp_f32_e32 v100, v100
	v_exp_f32_e32 v101, v101
	v_mfma_f32_32x32x16_bf16 v[16:31], v[176:179], v[212:215], v[16:31]
	v_cvt_pk_bf16_f32 v176, v96, v97
	v_cvt_pk_bf16_f32 v177, v98, v99
	v_exp_f32_e32 v96, v102
	v_exp_f32_e32 v97, v103
	s_waitcnt lgkmcnt(0)
	v_mfma_f32_32x32x16_bf16 v[48:63], v[172:175], v[120:123], v[48:63]
	v_cvt_pk_bf16_f32 v178, v100, v101
	v_cvt_pk_bf16_f32 v179, v96, v97
	v_exp_f32_e32 v98, v104
	v_exp_f32_e32 v99, v105
	v_mfma_f32_32x32x16_bf16 v[32:47], v[172:175], v[124:127], v[32:47]
	v_exp_f32_e32 v96, v106
	v_exp_f32_e32 v97, v107
	s_waitcnt vmcnt(3)
	ds_write_b128 v206, v[152:155] offset:0
	global_load_dwordx4 v[152:155], v247, s[100:101] offset:2048
	v_mfma_f32_32x32x16_bf16 v[0:15], v[172:175], v[252:255], v[0:15]
	v_exp_f32_e32 v100, v108
	v_exp_f32_e32 v101, v109
	v_mfma_f32_32x32x16_bf16 v[16:31], v[172:175], v[216:219], v[16:31]
	v_cvt_pk_bf16_f32 v172, v98, v99
	v_cvt_pk_bf16_f32 v173, v96, v97
	v_exp_f32_e32 v102, v110
	v_exp_f32_e32 v103, v111
	v_cvt_pk_bf16_f32 v174, v100, v101
	v_cvt_pk_bf16_f32 v175, v102, v103
	s_add_i32 s5, s5, 1
	s_cmp_lg_u32 s92, s5
	s_cbranch_scc0 .Lunr0_x1
; #define SBAR() __builtin_amdgcn_sched_barrier(0)
; template <bool SAFE> ...
;   bf16x8 kb[8];
; #pragma unroll
;   for (int d0 = 0; d0 < 4; ++d0) { const int cb = (cb0 + d0 * 16 + hi * 8) * 2;
;     kb[2 * d0] = *reinterpret_cast<const bf16x8*>((const char*)Ks + KSWZ(r32, cb));
;     kb[2 * d0 + 1] = *reinterpret_cast<const bf16x8*>((const char*)Ks + KSWZ(32 + r32, cb)); }
;   VFrag fa, fb;
;   vfrag_issue<0>(fa, vb);
;   p0 = MFMA32(kb[0], qr[0], cinit); p1 = MFMA32(kb[1], qr[0], cinit);
; #pragma unroll
;   for (int d0 = 1; d0 < 4; ++d0) { p0 = MFMA32(kb[2 * d0], qr[d0], p0); p1 = MFMA32(kb[2 * d0 + 1], qr[d0], p1); }
;   SBAR();
;   unsigned a0, a1, b0, b1; ps = 0.f;
;   fused_ks<0, SAFE>(o, lacc, vb, fa, fb, p0, p1, ps, a0, a1, b0, b1, pa0, pa1, pa2, pa3, st, sd, dow, ones);
;   fused_ks<1, SAFE>(o, lacc, vb, fb, fa, p0, p1, ps, a0, a1, b0, b1, pa0, pa1, pa2, pa3, st, sd, dow, ones);
;   fused_ks<2, SAFE>(o, lacc, vb, fa, fb, p0, p1, ps, a0, a1, b0, b1, pa0, pa1, pa2, pa3, st, sd, dow, ones);
;   fused_ks<3, SAFE>(o, lacc, vb, fb, fa, p0, p1, ps, a0, a1, b0, b1, pa0, pa1, pa2, pa3, st, sd, dow, ones);
;   SM2_UNIT(7);
;   if constexpr (SAFE) { auto rr = __builtin_amdgcn_permlane32_swap(__float_as_uint(ps), __float_as_uint(ps), false, false);
;     ps = __uint_as_float(rr[0]) + __uint_as_float(rr[1]); }
;   SBAR();
; }
; template <bool SAFE>
; __device__ __forceinline__ void diff_core(const bf16* __restrict__ Kh, const bf16* __restrict__ Vh, const int NT, const bf16x8* qr, char* lds,
;                                           const int wid, const int lane_unused, f32x16* o, f32x16& lacc, float& l_reg) {
;     ...
;   for (int j = 1; j < NT; ++j) {
;     const bool dow = true;
;     const bf16* Kc = (const bf16*)((const char*)K_lds + bc * SHM_K);
;     StgDst sd;
;     sd.v0 = (char*)V_lds + bn * SHM_V + vst0; sd.v1 = (char*)V_lds + bn * SHM_V + vst1;
;     sd.k0 = (char*)K_lds + bn * SHM_K + kw0;  sd.k1 = (char*)K_lds + bn * SHM_K + kw1;
;     tile_step<SAFE>(o, lacc, Kc, vb0 + bp * SHM_V, qr, rk, hi, cb0, p0, p1, cinit, ps, pa0, pa1, pa2, pa3, sr_[0], sd, dow, ones);
;     SLOAD(0, min(j + 2, NT - 1) * 64);
;     SBAR();
;     if constexpr (SAFE) FIXUP(Kc, false);
;     asm volatile("s_waitcnt lgkmcnt(0)" ::: "memory"); __builtin_amdgcn_s_barrier(); asm volatile("" ::: "memory");
;     const int t_ = bp; bp = bc; bc = bn; bn = t_;
	ds_read_b128 v[212:215], v77 offset:0
	ds_read_b128 v[216:219], v77 offset:8192
	s_add_i32 s98, s5, 2
	s_min_i32 s98, s98, s93
	s_mul_i32 s98, s98, 0x60000
	s_add_u32 s98, s10, s98
	s_addc_u32 s99, s11, 0
	s_add_u32 s100, s98, 0x30000
	s_addc_u32 s101, s99, 0
	v_mfma_f32_32x32x16_bf16 v[112:127], v[68:71], v[132:135], v[80:95]
	v_mfma_f32_32x32x16_bf16 v[96:111], v[72:75], v[132:135], v[80:95]
	ds_read_b128 v[68:71], v78 offset:0
	ds_read_b128 v[72:75], v78 offset:8192
	v_mfma_f32_16x16x32_bf16 v[64:67], v[180:183], v[148:151], v[64:67]
	s_waitcnt lgkmcnt(3)
	v_mfma_f32_32x32x16_bf16 v[112:127], v[212:215], v[136:139], v[112:127]
	ds_read_b128 v[212:215], v79 offset:0
	s_waitcnt vmcnt(3)
	ds_write_b128 v188, v[166:169] offset:16384
	global_load_dwordx4 v[166:169], v247, s[98:99] offset:1024
	s_waitcnt lgkmcnt(4)
	v_mfma_f32_32x32x16_bf16 v[96:111], v[216:219], v[136:139], v[96:111]
	ds_read_b128 v[216:219], v79 offset:8192
	v_mfma_f32_16x16x32_bf16 v[64:67], v[184:187], v[148:151], v[64:67]
	s_waitcnt lgkmcnt(4)
	v_mfma_f32_32x32x16_bf16 v[112:127], v[68:71], v[140:143], v[112:127]
	ds_read_b64_tr_b16 v[220:221], v211 offset:32768
	ds_read_b64_tr_b16 v[222:223], v211 offset:34816
	s_waitcnt vmcnt(3)
	ds_write_b128 v189, v[162:165] offset:16384
	global_load_dwordx4 v[162:165], v247, s[100:101] offset:1024
	v_mfma_f32_16x16x32_bf16 v[64:67], v[176:179], v[148:151], v[64:67]
	s_waitcnt lgkmcnt(6)
	v_mfma_f32_32x32x16_bf16 v[96:111], v[72:75], v[140:143], v[96:111]
	v_mfma_f32_16x16x32_bf16 v[64:67], v[172:175], v[148:151], v[64:67]
	s_waitcnt lgkmcnt(5)
	v_mfma_f32_32x32x16_bf16 v[112:127], v[212:215], v[144:147], v[112:127]
	ds_read_b64_tr_b16 v[212:213], v211 offset:33280
	ds_read_b64_tr_b16 v[214:215], v211 offset:35328
	ds_read_b64_tr_b16 v[224:225], v211 offset:33792
	ds_read_b64_tr_b16 v[226:227], v211 offset:35840
	ds_read_b64_tr_b16 v[228:229], v211 offset:34304
	ds_read_b64_tr_b16 v[230:231], v211 offset:36352
	s_waitcnt lgkmcnt(7)
	v_mfma_f32_32x32x16_bf16 v[96:111], v[216:219], v[144:147], v[96:111]
	ds_read_b64_tr_b16 v[216:217], v211 offset:36864
	ds_read_b64_tr_b16 v[218:219], v211 offset:38912
	ds_read_b64_tr_b16 v[232:233], v211 offset:37376
	ds_read_b64_tr_b16 v[234:235], v211 offset:39424
	ds_read_b64_tr_b16 v[236:237], v211 offset:37888
	ds_read_b64_tr_b16 v[238:239], v211 offset:39936
	ds_read_b64_tr_b16 v[240:241], v211 offset:38400
	ds_read_b64_tr_b16 v[242:243], v211 offset:40448
	s_waitcnt lgkmcnt(8)
	v_mfma_f32_32x32x16_bf16 v[48:63], v[180:183], v[220:223], v[48:63]
	s_nop 0
	v_exp_f32_e32 v112, v112
	v_exp_f32_e32 v113, v113
	v_mfma_f32_32x32x16_bf16 v[32:47], v[180:183], v[212:215], v[32:47]
	v_exp_f32_e32 v114, v114
	v_exp_f32_e32 v115, v115
	v_mfma_f32_32x32x16_bf16 v[0:15], v[180:183], v[224:227], v[0:15]
	v_exp_f32_e32 v171, v116
	v_exp_f32_e32 v220, v117
	v_mfma_f32_32x32x16_bf16 v[16:31], v[180:183], v[228:231], v[16:31]
	v_exp_f32_e32 v221, v118
	v_exp_f32_e32 v222, v119
	v_cvt_pk_bf16_f32 v180, v112, v113
	v_cvt_pk_bf16_f32 v181, v114, v115
	ds_read_b64_tr_b16 v[112:113], v211 offset:40960
	ds_read_b64_tr_b16 v[114:115], v211 offset:43008
	ds_read_b64_tr_b16 v[116:117], v211 offset:41472
	ds_read_b64_tr_b16 v[118:119], v211 offset:43520
	ds_read_b64_tr_b16 v[248:249], v211 offset:41984
	ds_read_b64_tr_b16 v[250:251], v211 offset:44032
	ds_read_b64_tr_b16 v[212:213], v211 offset:42496
	ds_read_b64_tr_b16 v[214:215], v211 offset:44544
	s_waitcnt lgkmcnt(8)
	v_mfma_f32_32x32x16_bf16 v[48:63], v[184:187], v[216:219], v[48:63]
	v_cvt_pk_bf16_f32 v182, v171, v220
	v_cvt_pk_bf16_f32 v183, v221, v222
	v_exp_f32_e32 v120, v120
	v_exp_f32_e32 v121, v121
	v_mfma_f32_32x32x16_bf16 v[32:47], v[184:187], v[232:235], v[32:47]
	v_exp_f32_e32 v122, v122
	v_exp_f32_e32 v123, v123
	v_mfma_f32_32x32x16_bf16 v[0:15], v[184:187], v[236:239], v[0:15]
	v_exp_f32_e32 v160, v124
	v_exp_f32_e32 v161, v125
	v_mfma_f32_32x32x16_bf16 v[16:31], v[184:187], v[240:243], v[16:31]
	v_exp_f32_e32 v220, v126
	v_exp_f32_e32 v221, v127
	v_cvt_pk_bf16_f32 v184, v120, v121
	v_cvt_pk_bf16_f32 v185, v122, v123
	s_waitcnt lgkmcnt(0)
	s_barrier
	v_mfma_f32_32x32x16_bf16 v[48:63], v[176:179], v[112:115], v[48:63]
	ds_read_b128 v[68:71], v76 offset:16384
	ds_read_b128 v[72:75], v76 offset:24576
	ds_read_b64_tr_b16 v[120:121], v211 offset:45056
	ds_read_b64_tr_b16 v[122:123], v211 offset:47104
	ds_read_b64_tr_b16 v[124:125], v211 offset:45568
	ds_read_b64_tr_b16 v[126:127], v211 offset:47616
	ds_read_b64_tr_b16 v[252:253], v211 offset:46080
	ds_read_b64_tr_b16 v[254:255], v211 offset:48128
	ds_read_b64_tr_b16 v[216:217], v211 offset:46592
	ds_read_b64_tr_b16 v[218:219], v211 offset:48640
	v_cvt_pk_bf16_f32 v186, v160, v161
	v_cvt_pk_bf16_f32 v187, v220, v221
	v_exp_f32_e32 v96, v96
	v_exp_f32_e32 v97, v97
	v_mfma_f32_32x32x16_bf16 v[32:47], v[176:179], v[116:119], v[32:47]
	v_exp_f32_e32 v98, v98
	v_exp_f32_e32 v99, v99
	s_waitcnt vmcnt(3)
	ds_write_b128 v205, v[156:159] offset:16384
	global_load_dwordx4 v[156:159], v247, s[98:99] offset:2048
	v_mfma_f32_32x32x16_bf16 v[0:15], v[176:179], v[248:251], v[0:15]
	v_exp_f32_e32 v100, v100
	v_exp_f32_e32 v101, v101
	v_mfma_f32_32x32x16_bf16 v[16:31], v[176:179], v[212:215], v[16:31]
	v_cvt_pk_bf16_f32 v176, v96, v97
	v_cvt_pk_bf16_f32 v177, v98, v99
	v_exp_f32_e32 v96, v102
	v_exp_f32_e32 v97, v103
	s_waitcnt lgkmcnt(0)
	v_mfma_f32_32x32x16_bf16 v[48:63], v[172:175], v[120:123], v[48:63]
	v_cvt_pk_bf16_f32 v178, v100, v101
	v_cvt_pk_bf16_f32 v179, v96, v97
	v_exp_f32_e32 v98, v104
	v_exp_f32_e32 v99, v105
	v_mfma_f32_32x32x16_bf16 v[32:47], v[172:175], v[124:127], v[32:47]
	v_exp_f32_e32 v96, v106
	v_exp_f32_e32 v97, v107
	s_waitcnt vmcnt(3)
	ds_write_b128 v206, v[152:155] offset:16384
	global_load_dwordx4 v[152:155], v247, s[100:101] offset:2048
	v_mfma_f32_32x32x16_bf16 v[0:15], v[172:175], v[252:255], v[0:15]
	v_exp_f32_e32 v100, v108
	v_exp_f32_e32 v101, v109
	v_mfma_f32_32x32x16_bf16 v[16:31], v[172:175], v[216:219], v[16:31]
	v_cvt_pk_bf16_f32 v172, v98, v99
	v_cvt_pk_bf16_f32 v173, v96, v97
	v_exp_f32_e32 v102, v110
	v_exp_f32_e32 v103, v111
	v_cvt_pk_bf16_f32 v174, v100, v101
	v_cvt_pk_bf16_f32 v175, v102, v103
	s_add_i32 s5, s5, 1
	s_cmp_lg_u32 s92, s5
	s_cbranch_scc1 .LBB0_105
	s_mov_b32 s7, 0
	s_branch .Lunr0_join
; #define MFMA32(a, b, c) __builtin_amdgcn_mfma_f32_32x32x16_bf16(a, b, c, 0, 0, 0)
; template <bool SAFE>
; __device__ __forceinline__ void diff_core(const bf16* __restrict__ Kh, const bf16* __restrict__ Vh, const int NT, const bf16x8* qr, char* lds,
;                                           const int wid, const int lane_unused, f32x16* o, f32x16& lacc, float& l_reg) {
;     ...
;   pv_d0(o, vb0 + bp * SHM_V, pa0, pa1, pa2, pa3);
;   if constexpr (!SAFE) {
;     lacc = MFMA32(pa0, ones, lacc); lacc = MFMA32(pa1, ones, lacc); lacc = MFMA32(pa2, ones, lacc); lacc = MFMA32(pa3, ones, lacc); }
; __device__ __forceinline__ void diff_attn_item(const bf16* __restrict__ qkv, bf16* __restrict__ mix, const float* __restrict__ dg,
;                                int tok0  , int key0  , int seq, int head, float lam, float oscale, const int W) {
;     ...
;     bool bad = (FORCE_SAFE != 0);
; #pragma unroll
;     for (int r = 0; r < 16; ++r) bad = bad || !(lacc[r] < 1.0e30f);
;     if (lane == 0) flag_l[wid] = __any(bad) ? 1 : 0;
.Lunr0_x0:
	s_movk_i32 s7, 0x4000
	s_branch .Lunr0_join
.Lunr0_x1:
	s_mov_b32 s7, 0x8000
.Lunr0_join:
	v_mov_b32_e32 v160, v180
	v_mov_b32_e32 v161, v181
	v_mov_b32_e32 v170, v184
	v_mov_b32_e32 v171, v185
	v_mov_b32_e32 v180, v176
	v_mov_b32_e32 v181, v177
	v_mov_b32_e32 v188, v172
	v_mov_b32_e32 v189, v173
	s_waitcnt vmcnt(0)
	v_add_u32_e32 v168, s7, v211
	ds_read_b64_tr_b16 v[80:81], v168 offset:0
	ds_read_b64_tr_b16 v[82:83], v168 offset:0x800
	ds_read_b64_tr_b16 v[84:85], v168 offset:0x1000
	ds_read_b64_tr_b16 v[86:87], v168 offset:0x1800
	ds_read_b64_tr_b16 v[88:89], v168 offset:0x2000
	ds_read_b64_tr_b16 v[90:91], v168 offset:0x2800
	ds_read_b64_tr_b16 v[92:93], v168 offset:0x3000
	ds_read_b64_tr_b16 v[94:95], v168 offset:0x3800
	s_waitcnt lgkmcnt(0)
	s_waitcnt vmcnt(0)
	v_mov_b32_e32 v162, v182
	v_mov_b32_e32 v163, v183
	v_mov_b32_e32 v172, v186
	v_mov_b32_e32 v173, v187
	v_mov_b32_e32 v182, v178
	v_mov_b32_e32 v183, v179
	v_mov_b32_e32 v190, v174
	v_mov_b32_e32 v191, v175
	ds_read_b64_tr_b16 v[96:97], v168 offset:0x200
	ds_read_b64_tr_b16 v[98:99], v168 offset:0xa00
	ds_read_b64_tr_b16 v[100:101], v168 offset:0x1200
	ds_read_b64_tr_b16 v[102:103], v168 offset:0x1a00
	ds_read_b64_tr_b16 v[104:105], v168 offset:0x2200
	ds_read_b64_tr_b16 v[106:107], v168 offset:0x2a00
	ds_read_b64_tr_b16 v[108:109], v168 offset:0x3200
	ds_read_b64_tr_b16 v[110:111], v168 offset:0x3a00
	s_waitcnt lgkmcnt(0)
	ds_read_b64_tr_b16 v[112:113], v168 offset:0x400
	ds_read_b64_tr_b16 v[114:115], v168 offset:0xc00
	ds_read_b64_tr_b16 v[116:117], v168 offset:0x1400
	ds_read_b64_tr_b16 v[118:119], v168 offset:0x1c00
	ds_read_b64_tr_b16 v[120:121], v168 offset:0x2400
	ds_read_b64_tr_b16 v[122:123], v168 offset:0x2c00
	ds_read_b64_tr_b16 v[124:125], v168 offset:0x3400
	ds_read_b64_tr_b16 v[126:127], v168 offset:0x3c00
	s_waitcnt lgkmcnt(0)
	ds_read_b64_tr_b16 v[152:153], v168 offset:0x600
	ds_read_b64_tr_b16 v[154:155], v168 offset:0xe00
	ds_read_b64_tr_b16 v[156:157], v168 offset:0x1600
	ds_read_b64_tr_b16 v[158:159], v168 offset:0x1e00
	ds_read_b64_tr_b16 v[164:165], v168 offset:0x2600
	ds_read_b64_tr_b16 v[166:167], v168 offset:0x2e00
	ds_read_b64_tr_b16 v[174:175], v168 offset:0x3600
	ds_read_b64_tr_b16 v[176:177], v168 offset:0x3e00
	s_waitcnt lgkmcnt(0)
	v_mfma_f32_16x16x32_bf16 v[64:67], v[160:163], v[148:151], v[64:67]
	v_cmp_eq_u32_e32 vcc, 0, v200
	v_mfma_f32_32x32x16_bf16 v[48:63], v[160:163], v[80:83], v[48:63]
	v_mfma_f32_32x32x16_bf16 v[32:47], v[160:163], v[96:99], v[32:47]
	v_mfma_f32_32x32x16_bf16 v[0:15], v[160:163], v[112:115], v[0:15]
	v_mfma_f32_32x32x16_bf16 v[16:31], v[160:163], v[152:155], v[16:31]
	v_mfma_f32_16x16x32_bf16 v[64:67], v[170:173], v[148:151], v[64:67]
	v_mfma_f32_32x32x16_bf16 v[48:63], v[170:173], v[84:87], v[48:63]
	v_mfma_f32_32x32x16_bf16 v[32:47], v[170:173], v[100:103], v[32:47]
	v_mfma_f32_32x32x16_bf16 v[0:15], v[170:173], v[116:119], v[0:15]
	v_mfma_f32_32x32x16_bf16 v[16:31], v[170:173], v[156:159], v[16:31]
	v_mfma_f32_16x16x32_bf16 v[64:67], v[180:183], v[148:151], v[64:67]
	v_mfma_f32_32x32x16_bf16 v[48:63], v[180:183], v[88:91], v[48:63]
	v_mfma_f32_32x32x16_bf16 v[32:47], v[180:183], v[104:107], v[32:47]
	v_mfma_f32_32x32x16_bf16 v[0:15], v[180:183], v[120:123], v[0:15]
	v_mfma_f32_32x32x16_bf16 v[16:31], v[180:183], v[164:167], v[16:31]
	v_mfma_f32_16x16x32_bf16 v[64:67], v[188:191], v[148:151], v[64:67]
	v_mfma_f32_32x32x16_bf16 v[48:63], v[188:191], v[92:95], v[48:63]
	v_mfma_f32_32x32x16_bf16 v[32:47], v[188:191], v[108:111], v[32:47]
	v_mfma_f32_32x32x16_bf16 v[0:15], v[188:191], v[124:127], v[0:15]
	v_mfma_f32_32x32x16_bf16 v[16:31], v[188:191], v[174:177], v[16:31]
	v_and_b32_e32 v248, 15, v200
	v_lshrrev_b32_e32 v249, 4, v200
	v_and_b32_e32 v250, 1, v200
	v_lshlrev_b32_e32 v249, 4, v249
	v_lshl_add_u32 v249, v250, 6, v249
	v_add_u32_e32 v249, s62, v249
	v_cmp_gt_u32_e64 s[98:99], 2, v248
	v_lshl_add_u32 v250, v198, 4, s62
	s_nop 7
	s_and_saveexec_b64 s[100:101], s[98:99]
	ds_write_b128 v249, v[64:67]
	s_mov_b64 exec, s[100:101]
	s_waitcnt lgkmcnt(0)
	ds_read_b128 v[64:67], v250
	ds_read_b128 v[68:71], v250 offset:32
	ds_read_b128 v[72:75], v250 offset:64
	ds_read_b128 v[76:79], v250 offset:96
	s_waitcnt lgkmcnt(0)
	s_and_saveexec_b64 s[6:7], vcc
	s_cbranch_execz .LBB0_108
	s_nop 5
	v_cmp_ngt_f32_e32 vcc, s85, v64
	v_cmp_ngt_f32_e64 s[4:5], s85, v65
	s_or_b64 s[4:5], vcc, s[4:5]
	v_cmp_ngt_f32_e32 vcc, s85, v66
	s_or_b64 s[4:5], s[4:5], vcc
	v_cmp_ngt_f32_e32 vcc, s85, v67
	s_or_b64 s[4:5], s[4:5], vcc
	v_cmp_ngt_f32_e32 vcc, s85, v68
	s_or_b64 s[4:5], s[4:5], vcc
	v_cmp_ngt_f32_e32 vcc, s85, v69
	s_or_b64 s[4:5], s[4:5], vcc
	v_cmp_ngt_f32_e32 vcc, s85, v70
	s_or_b64 s[4:5], s[4:5], vcc
	v_cmp_ngt_f32_e32 vcc, s85, v71
	s_or_b64 s[4:5], s[4:5], vcc
	v_cmp_ngt_f32_e32 vcc, s85, v72
	s_or_b64 s[4:5], s[4:5], vcc
	v_cmp_ngt_f32_e32 vcc, s85, v73
	s_or_b64 s[4:5], s[4:5], vcc
	v_cmp_ngt_f32_e32 vcc, s85, v74
	s_or_b64 s[4:5], s[4:5], vcc
	v_cmp_ngt_f32_e32 vcc, s85, v75
	s_or_b64 s[4:5], s[4:5], vcc
	v_cmp_ngt_f32_e32 vcc, s85, v76
	s_or_b64 s[4:5], s[4:5], vcc
	v_cmp_ngt_f32_e32 vcc, s85, v77
	s_or_b64 s[4:5], s[4:5], vcc
	v_cmp_ngt_f32_e32 vcc, s85, v78
	s_or_b64 s[4:5], s[4:5], vcc
	v_cmp_ngt_f32_e32 vcc, s85, v79
	s_or_b64 s[4:5], s[4:5], vcc
	v_cndmask_b32_e64 v80, 0, 1, s[4:5]
	v_cmp_ne_u32_e32 vcc, 0, v80
	s_cmp_lg_u64 vcc, 0
	s_cselect_b64 s[4:5], -1, 0
	v_cndmask_b32_e64 v80, 0, 1, s[4:5]
	v_readlane_b32 s4, v246, 17
	s_nop 1
	v_mov_b32_e32 v81, s4
	ds_write_b32 v81, v80

; #define SLOAD(i, k0) do { sr_[i].vs0 = *reinterpret_cast<const bf16x8*>(&Vh[(size_t)((k0) + sr) * LDQ + sc]); sr_[i].vs1 = *reinterpret_cast<const bf16x8*>(&Vh[(size_t)((k0) + 32 + sr) * LDQ + sc]); \
;     sr_[i].ks0 = *reinterpret_cast<const bf16x8*>(&Kh[(size_t)((k0) + sr) * LDQ + sc]); sr_[i].ks1 = *reinterpret_cast<const bf16x8*>(&Kh[(size_t)((k0) + 32 + sr) * LDQ + sc]); } while (0)
; #define SWRITE(b, i) do { *(bf16x8*)((char*)V_lds + (b) * SHM_V + vst0) = sr_[i].vs0;          \
;     *(bf16x8*)((char*)V_lds + (b) * SHM_V + vst1) = sr_[i].vs1; int kc = sc * 2;               \
;     *(bf16x8*)((char*)K_lds + (b) * SHM_K + KSWZ(sr, kc)) = sr_[i].ks0;                       \
;     *(bf16x8*)((char*)K_lds + (b) * SHM_K + KSWZ(32 + sr, kc)) = sr_[i].ks1; } while (0)
; template <bool SAFE>
; __device__ __forceinline__ void diff_core(const bf16* __restrict__ Kh, const bf16* __restrict__ Vh, const int NT, const bf16x8* qr, char* lds,
;                                           const int wid, const int lane_unused, f32x16* o, f32x16& lacc, float& l_reg) {
;     ...
;   const int kw0 = KSWZ(sr, sc * 2), kw1 = KSWZ(32 + sr, sc * 2);
;   SLOAD(0, 0); asm volatile("s_waitcnt vmcnt(0)" ::: "memory"); SWRITE(0, 0);
;   SLOAD(0, 64); asm volatile("s_waitcnt vmcnt(0)" ::: "memory"); SWRITE(1, 0); __syncthreads();
;   SLOAD(0, 128);
;   FIXUP(K_lds, true);
;   int bc = 1, bp = 0, bn = 2;
.LBB0_315:
	s_or_b64 exec, exec, s[6:7]
	v_and_b32_e32 v200, 63, v0
	v_lshlrev_b32_e32 v0, 4, v2
	v_and_b32_e32 v0, 0xc0, v0
	v_and_or_b32 v0, v1, 24, v0
	v_and_b32_e32 v2, 32, v4
	v_and_b32_e32 v1, 0x100, v1
	s_waitcnt lgkmcnt(0)
	v_add_u32_e32 v9, s62, v3
	v_or3_b32 v8, v0, v2, v1
	ds_read_b128 v[0:3], v9 offset:192
	ds_read_b128 v[4:7], v9 offset:224
	ds_read_b128 v[50:53], v9 offset:128
	ds_read_b128 v[54:57], v9 offset:160
	v_sub_f32_e32 v16, v16, v48
	v_sub_f32_e32 v17, v17, v48
	v_sub_f32_e32 v18, v18, v48
	v_sub_f32_e32 v19, v19, v48
	v_sub_f32_e32 v20, v20, v48
	v_sub_f32_e32 v21, v21, v48
	v_sub_f32_e32 v22, v22, v48
	v_sub_f32_e32 v23, v23, v48
	v_sub_f32_e32 v24, v24, v48
	v_sub_f32_e32 v25, v25, v48
	v_sub_f32_e32 v26, v26, v48
	v_sub_f32_e32 v27, v27, v48
	v_sub_f32_e32 v28, v28, v48
	v_sub_f32_e32 v29, v29, v48
	v_sub_f32_e32 v30, v30, v48
	v_sub_f32_e32 v31, v31, v48
	v_sub_f32_e32 v32, v32, v48
	v_sub_f32_e32 v33, v33, v48
	v_sub_f32_e32 v34, v34, v48
	v_sub_f32_e32 v35, v35, v48
	v_sub_f32_e32 v36, v36, v48
	v_sub_f32_e32 v37, v37, v48
	v_sub_f32_e32 v38, v38, v48
	v_sub_f32_e32 v39, v39, v48
	v_sub_f32_e32 v40, v40, v48
	v_sub_f32_e32 v41, v41, v48
	v_sub_f32_e32 v42, v42, v48
	v_sub_f32_e32 v43, v43, v48
	v_sub_f32_e32 v44, v44, v48
	v_sub_f32_e32 v45, v45, v48
	v_sub_f32_e32 v46, v46, v48
	v_sub_f32_e32 v47, v47, v48
	v_exp_f32_e32 v16, v16
	v_exp_f32_e32 v17, v17
	v_exp_f32_e32 v18, v18
	v_exp_f32_e32 v19, v19
	v_exp_f32_e32 v20, v20
	v_exp_f32_e32 v21, v21
	v_exp_f32_e32 v22, v22
	v_exp_f32_e32 v23, v23
	v_exp_f32_e32 v24, v24
	v_exp_f32_e32 v25, v25
	v_exp_f32_e32 v26, v26
	v_exp_f32_e32 v27, v27
	v_exp_f32_e32 v28, v28
	v_exp_f32_e32 v29, v29
	v_exp_f32_e32 v30, v30
	v_exp_f32_e32 v31, v31
	v_exp_f32_e32 v32, v32
	v_exp_f32_e32 v33, v33
	v_exp_f32_e32 v34, v34
	v_exp_f32_e32 v35, v35
	v_exp_f32_e32 v36, v36
	v_exp_f32_e32 v37, v37
	v_exp_f32_e32 v38, v38
	v_exp_f32_e32 v39, v39
	v_exp_f32_e32 v40, v40
	v_exp_f32_e32 v41, v41
	v_exp_f32_e32 v42, v42
	v_exp_f32_e32 v43, v43
	v_exp_f32_e32 v44, v44
	v_exp_f32_e32 v45, v45
	v_exp_f32_e32 v46, v46
	v_exp_f32_e32 v47, v47
	s_lshl_b32 s20, s26, 7
	s_cmp_lg_u32 0, -1
	s_cselect_b32 s7, 0, 0
	s_waitcnt lgkmcnt(2)
	v_pk_mul_f32 v[14:15], v[6:7], 0 op_sel_hi:[1,0]
	v_xor_b32_e32 v80, 0x80000000, v48
	v_add_u32_e32 v211, s7, v8
	v_pk_mul_f32 v[10:11], v[2:3], 0 op_sel_hi:[1,0]
	s_waitcnt lgkmcnt(0)
	v_pk_mul_f32 v[6:7], v[56:57], 0 op_sel_hi:[1,0]
	v_pk_mul_f32 v[2:3], v[52:53], 0 op_sel_hi:[1,0]
	v_pk_mul_f32 v[12:13], v[4:5], 0 op_sel_hi:[1,0]
	v_pk_mul_f32 v[8:9], v[0:1], 0 op_sel_hi:[1,0]
	v_pk_mul_f32 v[4:5], v[54:55], 0 op_sel_hi:[1,0]
	v_pk_mul_f32 v[0:1], v[50:51], 0 op_sel_hi:[1,0]
	v_cvt_pk_bf16_f32 v160, v16, v17
	v_cvt_pk_bf16_f32 v161, v18, v19
	v_cvt_pk_bf16_f32 v182, v20, v21
	v_cvt_pk_bf16_f32 v183, v22, v23
	v_cvt_pk_bf16_f32 v170, v24, v25
	v_cvt_pk_bf16_f32 v171, v26, v27
	v_cvt_pk_bf16_f32 v186, v28, v29
	v_cvt_pk_bf16_f32 v187, v30, v31
	v_cvt_pk_bf16_f32 v180, v32, v33
	v_cvt_pk_bf16_f32 v181, v34, v35
	v_cvt_pk_bf16_f32 v178, v36, v37
	v_cvt_pk_bf16_f32 v179, v38, v39
	v_cvt_pk_bf16_f32 v188, v40, v41
	v_cvt_pk_bf16_f32 v189, v42, v43
	v_cvt_pk_bf16_f32 v174, v44, v45
	v_cvt_pk_bf16_f32 v175, v46, v47
	v_mov_b32_e32 v64, 0
	v_mov_b64_e32 v[46:47], v[14:15]
	v_mov_b64_e32 v[62:63], v[14:15]
	v_mov_b64_e32 v[30:31], v[14:15]
	v_mov_b32_e32 v81, v80
	v_mov_b32_e32 v82, v80
	v_mov_b32_e32 v83, v80
	v_mov_b32_e32 v84, v80
	v_mov_b32_e32 v85, v80
	v_mov_b32_e32 v86, v80
	v_mov_b32_e32 v87, v80
	v_mov_b32_e32 v88, v80
	v_mov_b32_e32 v89, v80
	v_mov_b32_e32 v90, v80
	v_mov_b32_e32 v91, v80
	v_mov_b32_e32 v92, v80
	v_mov_b32_e32 v93, v80
	v_mov_b32_e32 v94, v80
	v_mov_b32_e32 v95, v80
	s_mov_b32 s6, 0
	s_mov_b32 s7, 1
	v_lshl_add_u64 v[190:191], s[14:15], 0, v[194:195]
	v_mad_u32_u24 v247, v201, s41, v194
	s_add_i32 s64, s55, -1
	s_mov_b32 s27, 2
	v_mov_b64_e32 v[44:45], v[12:13]
	v_mov_b64_e32 v[42:43], v[10:11]
	v_mov_b64_e32 v[40:41], v[8:9]
	v_mov_b64_e32 v[38:39], v[6:7]
	v_mov_b64_e32 v[36:37], v[4:5]
	v_mov_b64_e32 v[34:35], v[2:3]
	v_mov_b64_e32 v[32:33], v[0:1]
	v_mov_b64_e32 v[60:61], v[12:13]
	v_mov_b64_e32 v[58:59], v[10:11]
	v_mov_b64_e32 v[56:57], v[8:9]
	v_mov_b64_e32 v[54:55], v[6:7]
	v_mov_b64_e32 v[52:53], v[4:5]
	v_mov_b64_e32 v[50:51], v[2:3]
	v_mov_b64_e32 v[48:49], v[0:1]
	v_mov_b64_e32 v[28:29], v[12:13]
	v_mov_b64_e32 v[26:27], v[10:11]
	v_mov_b64_e32 v[24:25], v[8:9]
	v_mov_b64_e32 v[22:23], v[6:7]
	v_mov_b64_e32 v[20:21], v[4:5]
	v_mov_b64_e32 v[18:19], v[2:3]
	v_mov_b64_e32 v[16:17], v[0:1]
	s_mov_b32 s10, 1
	v_mov_b32_e32 v65, v64
	v_mov_b32_e32 v66, v64
	v_mov_b32_e32 v67, v64
	v_mov_b32_e32 v68, v64
	v_mov_b32_e32 v69, v64
	v_mov_b32_e32 v70, v64
	v_mov_b32_e32 v71, v64
	v_mov_b32_e32 v72, v64
	v_mov_b32_e32 v73, v64
	v_mov_b32_e32 v74, v64
	v_mov_b32_e32 v75, v64
	v_mov_b32_e32 v76, v64
	v_mov_b32_e32 v77, v64
	v_mov_b32_e32 v78, v64
	v_mov_b32_e32 v79, v64
	v_mov_b32_e32 v176, v180
	v_mov_b32_e32 v177, v181
	v_mov_b32_e32 v180, v160
	v_mov_b32_e32 v181, v161
	v_mov_b32_e32 v184, v170
	v_mov_b32_e32 v185, v171
	v_mov_b32_e32 v172, v188
	v_mov_b32_e32 v173, v189
	v_add_u32_e32 v76, 0xc000, v207
	v_add_u32_e32 v77, 0xc000, v208
	v_add_u32_e32 v78, 0xc000, v209
	v_add_u32_e32 v79, 0xc000, v210
	v_add_u32_e32 v188, 0xc000, v203
	v_add_u32_e32 v189, 0xc000, v204
	ds_read_b128 v[68:71], v76 offset:16384
	ds_read_b128 v[72:75], v76 offset:24576
	s_waitcnt lgkmcnt(0)
; #define SBAR() __builtin_amdgcn_sched_barrier(0)
; template <bool SAFE> ...
;   bf16x8 kb[8];
; #pragma unroll
;   for (int d0 = 0; d0 < 4; ++d0) { const int cb = (cb0 + d0 * 16 + hi * 8) * 2;
;     kb[2 * d0] = *reinterpret_cast<const bf16x8*>((const char*)Ks + KSWZ(r32, cb));
;     kb[2 * d0 + 1] = *reinterpret_cast<const bf16x8*>((const char*)Ks + KSWZ(32 + r32, cb)); }
;   VFrag fa, fb;
;   vfrag_issue<0>(fa, vb);
;   p0 = MFMA32(kb[0], qr[0], cinit); p1 = MFMA32(kb[1], qr[0], cinit);
; #pragma unroll
;   for (int d0 = 1; d0 < 4; ++d0) { p0 = MFMA32(kb[2 * d0], qr[d0], p0); p1 = MFMA32(kb[2 * d0 + 1], qr[d0], p1); }
;   SBAR();
;   unsigned a0, a1, b0, b1; ps = 0.f;
;   fused_ks<0, SAFE>(o, lacc, vb, fa, fb, p0, p1, ps, a0, a1, b0, b1, pa0, pa1, pa2, pa3, st, sd, dow, ones);
;   fused_ks<1, SAFE>(o, lacc, vb, fb, fa, p0, p1, ps, a0, a1, b0, b1, pa0, pa1, pa2, pa3, st, sd, dow, ones);
;   fused_ks<2, SAFE>(o, lacc, vb, fa, fb, p0, p1, ps, a0, a1, b0, b1, pa0, pa1, pa2, pa3, st, sd, dow, ones);
;   fused_ks<3, SAFE>(o, lacc, vb, fb, fa, p0, p1, ps, a0, a1, b0, b1, pa0, pa1, pa2, pa3, st, sd, dow, ones);
;   SM2_UNIT(7);
;   if constexpr (SAFE) { auto rr = __builtin_amdgcn_permlane32_swap(__float_as_uint(ps), __float_as_uint(ps), false, false);
;     ps = __uint_as_float(rr[0]) + __uint_as_float(rr[1]); }
;   SBAR();
; }
; template <bool SAFE>
; __device__ __forceinline__ void diff_core(const bf16* __restrict__ Kh, const bf16* __restrict__ Vh, const int NT, const bf16x8* qr, char* lds,
;                                           const int wid, const int lane_unused, f32x16* o, f32x16& lacc, float& l_reg) {
;     ...
;   for (int j = 1; j < NT; ++j) {
;     const bool dow = true;
;     const bf16* Kc = (const bf16*)((const char*)K_lds + bc * SHM_K);
;     StgDst sd;
;     sd.v0 = (char*)V_lds + bn * SHM_V + vst0; sd.v1 = (char*)V_lds + bn * SHM_V + vst1;
;     sd.k0 = (char*)K_lds + bn * SHM_K + kw0;  sd.k1 = (char*)K_lds + bn * SHM_K + kw1;
;     tile_step<SAFE>(o, lacc, Kc, vb0 + bp * SHM_V, qr, rk, hi, cb0, p0, p1, cinit, ps, pa0, pa1, pa2, pa3, sr_[0], sd, dow, ones);
;     SLOAD(0, min(j + 2, NT - 1) * 64);
;     SBAR();
;     if constexpr (SAFE) FIXUP(Kc, false);
;     asm volatile("s_waitcnt lgkmcnt(0)" ::: "memory"); __builtin_amdgcn_s_barrier(); asm volatile("" ::: "memory");
;     const int t_ = bp; bp = bc; bc = bn; bn = t_;
.LBB0_316:
	ds_read_b128 v[212:215], v77 offset:16384
	ds_read_b128 v[216:219], v77 offset:24576
	s_add_i32 s98, s7, 2
	s_min_i32 s98, s98, s64
	s_mul_i32 s98, s98, 0x60000
	s_add_u32 s98, s14, s98
	s_addc_u32 s99, s15, 0
	s_add_u32 s100, s98, 0x30000
	s_addc_u32 s101, s99, 0
	v_mfma_f32_32x32x16_bf16 v[112:127], v[68:71], v[132:135], v[80:95]
	v_mfma_f32_32x32x16_bf16 v[96:111], v[72:75], v[132:135], v[80:95]
	ds_read_b128 v[68:71], v78 offset:16384
	ds_read_b128 v[72:75], v78 offset:24576
	v_mfma_f32_16x16x32_bf16 v[64:67], v[180:183], v[148:151], v[64:67]
	s_waitcnt lgkmcnt(3)
	v_mfma_f32_32x32x16_bf16 v[112:127], v[212:215], v[136:139], v[112:127]
	ds_read_b128 v[212:215], v79 offset:16384
	s_waitcnt vmcnt(3)
	ds_write_b128 v188, v[166:169] offset:32768
	global_load_dwordx4 v[166:169], v247, s[98:99] offset:1024
	s_waitcnt lgkmcnt(4)
	v_mfma_f32_32x32x16_bf16 v[96:111], v[216:219], v[136:139], v[96:111]
	ds_read_b128 v[216:219], v79 offset:24576
	v_mfma_f32_16x16x32_bf16 v[64:67], v[184:187], v[148:151], v[64:67]
	s_waitcnt lgkmcnt(4)
	v_mfma_f32_32x32x16_bf16 v[112:127], v[68:71], v[140:143], v[112:127]
	ds_read_b64_tr_b16 v[220:221], v211 offset:0
	ds_read_b64_tr_b16 v[222:223], v211 offset:2048
	s_waitcnt vmcnt(3)
	ds_write_b128 v189, v[162:165] offset:32768
	global_load_dwordx4 v[162:165], v247, s[100:101] offset:1024
	v_mfma_f32_16x16x32_bf16 v[64:67], v[176:179], v[148:151], v[64:67]
	s_waitcnt lgkmcnt(6)
	v_mfma_f32_32x32x16_bf16 v[96:111], v[72:75], v[140:143], v[96:111]
	v_mfma_f32_16x16x32_bf16 v[64:67], v[172:175], v[148:151], v[64:67]
	s_waitcnt lgkmcnt(5)
	v_mfma_f32_32x32x16_bf16 v[112:127], v[212:215], v[144:147], v[112:127]
	ds_read_b64_tr_b16 v[212:213], v211 offset:512
	ds_read_b64_tr_b16 v[214:215], v211 offset:2560
	ds_read_b64_tr_b16 v[224:225], v211 offset:1024
	ds_read_b64_tr_b16 v[226:227], v211 offset:3072
	ds_read_b64_tr_b16 v[228:229], v211 offset:1536
	ds_read_b64_tr_b16 v[230:231], v211 offset:3584
	s_waitcnt lgkmcnt(7)
	v_mfma_f32_32x32x16_bf16 v[96:111], v[216:219], v[144:147], v[96:111]
	ds_read_b64_tr_b16 v[216:217], v211 offset:4096
	ds_read_b64_tr_b16 v[218:219], v211 offset:6144
	ds_read_b64_tr_b16 v[232:233], v211 offset:4608
	ds_read_b64_tr_b16 v[234:235], v211 offset:6656
	ds_read_b64_tr_b16 v[236:237], v211 offset:5120
	ds_read_b64_tr_b16 v[238:239], v211 offset:7168
	ds_read_b64_tr_b16 v[240:241], v211 offset:5632
	ds_read_b64_tr_b16 v[242:243], v211 offset:7680
	s_waitcnt lgkmcnt(8)
	v_mfma_f32_32x32x16_bf16 v[48:63], v[180:183], v[220:223], v[48:63]
	s_nop 0
	v_exp_f32_e32 v112, v112
	v_exp_f32_e32 v113, v113
	v_mfma_f32_32x32x16_bf16 v[32:47], v[180:183], v[212:215], v[32:47]
	v_exp_f32_e32 v114, v114
	v_exp_f32_e32 v115, v115
	v_mfma_f32_32x32x16_bf16 v[0:15], v[180:183], v[224:227], v[0:15]
	v_exp_f32_e32 v171, v116
	v_exp_f32_e32 v220, v117
	v_mfma_f32_32x32x16_bf16 v[16:31], v[180:183], v[228:231], v[16:31]
	v_exp_f32_e32 v221, v118
	v_exp_f32_e32 v222, v119
	v_cvt_pk_bf16_f32 v180, v112, v113
	v_cvt_pk_bf16_f32 v181, v114, v115
	ds_read_b64_tr_b16 v[112:113], v211 offset:8192
	ds_read_b64_tr_b16 v[114:115], v211 offset:10240
	ds_read_b64_tr_b16 v[116:117], v211 offset:8704
	ds_read_b64_tr_b16 v[118:119], v211 offset:10752
	ds_read_b64_tr_b16 v[248:249], v211 offset:9216
	ds_read_b64_tr_b16 v[250:251], v211 offset:11264
	ds_read_b64_tr_b16 v[212:213], v211 offset:9728
	ds_read_b64_tr_b16 v[214:215], v211 offset:11776
	s_waitcnt lgkmcnt(8)
	v_mfma_f32_32x32x16_bf16 v[48:63], v[184:187], v[216:219], v[48:63]
	v_cvt_pk_bf16_f32 v182, v171, v220
	v_cvt_pk_bf16_f32 v183, v221, v222
	v_exp_f32_e32 v120, v120
	v_exp_f32_e32 v121, v121
	v_mfma_f32_32x32x16_bf16 v[32:47], v[184:187], v[232:235], v[32:47]
	v_exp_f32_e32 v122, v122
	v_exp_f32_e32 v123, v123
	v_mfma_f32_32x32x16_bf16 v[0:15], v[184:187], v[236:239], v[0:15]
	v_exp_f32_e32 v160, v124
	v_exp_f32_e32 v161, v125
	v_mfma_f32_32x32x16_bf16 v[16:31], v[184:187], v[240:243], v[16:31]
	v_exp_f32_e32 v220, v126
	v_exp_f32_e32 v221, v127
	v_cvt_pk_bf16_f32 v184, v120, v121
	v_cvt_pk_bf16_f32 v185, v122, v123
	s_waitcnt lgkmcnt(0)
	s_barrier
	v_mfma_f32_32x32x16_bf16 v[48:63], v[176:179], v[112:115], v[48:63]
	ds_read_b128 v[68:71], v76 offset:32768
	ds_read_b128 v[72:75], v76 offset:40960
	ds_read_b64_tr_b16 v[120:121], v211 offset:12288
	ds_read_b64_tr_b16 v[122:123], v211 offset:14336
	ds_read_b64_tr_b16 v[124:125], v211 offset:12800
	ds_read_b64_tr_b16 v[126:127], v211 offset:14848
	ds_read_b64_tr_b16 v[252:253], v211 offset:13312
	ds_read_b64_tr_b16 v[254:255], v211 offset:15360
	ds_read_b64_tr_b16 v[216:217], v211 offset:13824
	ds_read_b64_tr_b16 v[218:219], v211 offset:15872
	v_cvt_pk_bf16_f32 v186, v160, v161
	v_cvt_pk_bf16_f32 v187, v220, v221
	v_exp_f32_e32 v96, v96
	v_exp_f32_e32 v97, v97
	v_mfma_f32_32x32x16_bf16 v[32:47], v[176:179], v[116:119], v[32:47]
	v_exp_f32_e32 v98, v98
	v_exp_f32_e32 v99, v99
	s_waitcnt vmcnt(3)
	ds_write_b128 v205, v[156:159] offset:32768
	global_load_dwordx4 v[156:159], v247, s[98:99] offset:2048
	v_mfma_f32_32x32x16_bf16 v[0:15], v[176:179], v[248:251], v[0:15]
	v_exp_f32_e32 v100, v100
	v_exp_f32_e32 v101, v101
	v_mfma_f32_32x32x16_bf16 v[16:31], v[176:179], v[212:215], v[16:31]
	v_cvt_pk_bf16_f32 v176, v96, v97
	v_cvt_pk_bf16_f32 v177, v98, v99
	v_exp_f32_e32 v96, v102
	v_exp_f32_e32 v97, v103
	s_waitcnt lgkmcnt(0)
	v_mfma_f32_32x32x16_bf16 v[48:63], v[172:175], v[120:123], v[48:63]
	v_cvt_pk_bf16_f32 v178, v100, v101
	v_cvt_pk_bf16_f32 v179, v96, v97
	v_exp_f32_e32 v98, v104
	v_exp_f32_e32 v99, v105
	v_mfma_f32_32x32x16_bf16 v[32:47], v[172:175], v[124:127], v[32:47]
	v_exp_f32_e32 v96, v106
	v_exp_f32_e32 v97, v107
	s_waitcnt vmcnt(3)
	ds_write_b128 v206, v[152:155] offset:32768
	global_load_dwordx4 v[152:155], v247, s[100:101] offset:2048
	v_mfma_f32_32x32x16_bf16 v[0:15], v[172:175], v[252:255], v[0:15]
	v_exp_f32_e32 v100, v108
	v_exp_f32_e32 v101, v109
	v_mfma_f32_32x32x16_bf16 v[16:31], v[172:175], v[216:219], v[16:31]
	v_cvt_pk_bf16_f32 v172, v98, v99
	v_cvt_pk_bf16_f32 v173, v96, v97
	v_exp_f32_e32 v102, v110
	v_exp_f32_e32 v103, v111
	v_cvt_pk_bf16_f32 v174, v100, v101
	v_cvt_pk_bf16_f32 v175, v102, v103
	s_add_i32 s7, s7, 1
	s_cmp_lg_u32 s55, s7
	s_cbranch_scc0 .Lunr1_x0
; #define SBAR() __builtin_amdgcn_sched_barrier(0)
; template <bool SAFE> ...
;   bf16x8 kb[8];
; #pragma unroll
;   for (int d0 = 0; d0 < 4; ++d0) { const int cb = (cb0 + d0 * 16 + hi * 8) * 2;
;     kb[2 * d0] = *reinterpret_cast<const bf16x8*>((const char*)Ks + KSWZ(r32, cb));
;     kb[2 * d0 + 1] = *reinterpret_cast<const bf16x8*>((const char*)Ks + KSWZ(32 + r32, cb)); }
;   VFrag fa, fb;
;   vfrag_issue<0>(fa, vb);
;   p0 = MFMA32(kb[0], qr[0], cinit); p1 = MFMA32(kb[1], qr[0], cinit);
; #pragma unroll
;   for (int d0 = 1; d0 < 4; ++d0) { p0 = MFMA32(kb[2 * d0], qr[d0], p0); p1 = MFMA32(kb[2 * d0 + 1], qr[d0], p1); }
;   SBAR();
;   unsigned a0, a1, b0, b1; ps = 0.f;
;   fused_ks<0, SAFE>(o, lacc, vb, fa, fb, p0, p1, ps, a0, a1, b0, b1, pa0, pa1, pa2, pa3, st, sd, dow, ones);
;   fused_ks<1, SAFE>(o, lacc, vb, fb, fa, p0, p1, ps, a0, a1, b0, b1, pa0, pa1, pa2, pa3, st, sd, dow, ones);
;   fused_ks<2, SAFE>(o, lacc, vb, fa, fb, p0, p1, ps, a0, a1, b0, b1, pa0, pa1, pa2, pa3, st, sd, dow, ones);
;   fused_ks<3, SAFE>(o, lacc, vb, fb, fa, p0, p1, ps, a0, a1, b0, b1, pa0, pa1, pa2, pa3, st, sd, dow, ones);
;   SM2_UNIT(7);
;   if constexpr (SAFE) { auto rr = __builtin_amdgcn_permlane32_swap(__float_as_uint(ps), __float_as_uint(ps), false, false);
;     ps = __uint_as_float(rr[0]) + __uint_as_float(rr[1]); }
;   SBAR();
; }
; template <bool SAFE>
; __device__ __forceinline__ void diff_core(const bf16* __restrict__ Kh, const bf16* __restrict__ Vh, const int NT, const bf16x8* qr, char* lds,
;                                           const int wid, const int lane_unused, f32x16* o, f32x16& lacc, float& l_reg) {
;     ...
;   for (int j = 1; j < NT; ++j) {
;     const bool dow = true;
;     const bf16* Kc = (const bf16*)((const char*)K_lds + bc * SHM_K);
;     StgDst sd;
;     sd.v0 = (char*)V_lds + bn * SHM_V + vst0; sd.v1 = (char*)V_lds + bn * SHM_V + vst1;
;     sd.k0 = (char*)K_lds + bn * SHM_K + kw0;  sd.k1 = (char*)K_lds + bn * SHM_K + kw1;
;     tile_step<SAFE>(o, lacc, Kc, vb0 + bp * SHM_V, qr, rk, hi, cb0, p0, p1, cinit, ps, pa0, pa1, pa2, pa3, sr_[0], sd, dow, ones);
;     SLOAD(0, min(j + 2, NT - 1) * 64);
;     SBAR();
;     if constexpr (SAFE) FIXUP(Kc, false);
;     asm volatile("s_waitcnt lgkmcnt(0)" ::: "memory"); __builtin_amdgcn_s_barrier(); asm volatile("" ::: "memory");
;     const int t_ = bp; bp = bc; bc = bn; bn = t_;
	ds_read_b128 v[212:215], v77 offset:32768
	ds_read_b128 v[216:219], v77 offset:40960
	s_add_i32 s98, s7, 2
	s_min_i32 s98, s98, s64
	s_mul_i32 s98, s98, 0x60000
	s_add_u32 s98, s14, s98
	s_addc_u32 s99, s15, 0
	s_add_u32 s100, s98, 0x30000
	s_addc_u32 s101, s99, 0
	v_mfma_f32_32x32x16_bf16 v[112:127], v[68:71], v[132:135], v[80:95]
	v_mfma_f32_32x32x16_bf16 v[96:111], v[72:75], v[132:135], v[80:95]
	ds_read_b128 v[68:71], v78 offset:32768
	ds_read_b128 v[72:75], v78 offset:40960
	v_mfma_f32_16x16x32_bf16 v[64:67], v[180:183], v[148:151], v[64:67]
	s_waitcnt lgkmcnt(3)
	v_mfma_f32_32x32x16_bf16 v[112:127], v[212:215], v[136:139], v[112:127]
	ds_read_b128 v[212:215], v79 offset:32768
	s_waitcnt vmcnt(3)
	ds_write_b128 v188, v[166:169] offset:0
	global_load_dwordx4 v[166:169], v247, s[98:99] offset:1024
	s_waitcnt lgkmcnt(4)
	v_mfma_f32_32x32x16_bf16 v[96:111], v[216:219], v[136:139], v[96:111]
	ds_read_b128 v[216:219], v79 offset:40960
	v_mfma_f32_16x16x32_bf16 v[64:67], v[184:187], v[148:151], v[64:67]
	s_waitcnt lgkmcnt(4)
	v_mfma_f32_32x32x16_bf16 v[112:127], v[68:71], v[140:143], v[112:127]
	ds_read_b64_tr_b16 v[220:221], v211 offset:16384
	ds_read_b64_tr_b16 v[222:223], v211 offset:18432
	s_waitcnt vmcnt(3)
	ds_write_b128 v189, v[162:165] offset:0
	global_load_dwordx4 v[162:165], v247, s[100:101] offset:1024
	v_mfma_f32_16x16x32_bf16 v[64:67], v[176:179], v[148:151], v[64:67]
	s_waitcnt lgkmcnt(6)
	v_mfma_f32_32x32x16_bf16 v[96:111], v[72:75], v[140:143], v[96:111]
	v_mfma_f32_16x16x32_bf16 v[64:67], v[172:175], v[148:151], v[64:67]
	s_waitcnt lgkmcnt(5)
	v_mfma_f32_32x32x16_bf16 v[112:127], v[212:215], v[144:147], v[112:127]
	ds_read_b64_tr_b16 v[212:213], v211 offset:16896
	ds_read_b64_tr_b16 v[214:215], v211 offset:18944
	ds_read_b64_tr_b16 v[224:225], v211 offset:17408
	ds_read_b64_tr_b16 v[226:227], v211 offset:19456
	ds_read_b64_tr_b16 v[228:229], v211 offset:17920
	ds_read_b64_tr_b16 v[230:231], v211 offset:19968
	s_waitcnt lgkmcnt(7)
	v_mfma_f32_32x32x16_bf16 v[96:111], v[216:219], v[144:147], v[96:111]
	ds_read_b64_tr_b16 v[216:217], v211 offset:20480
	ds_read_b64_tr_b16 v[218:219], v211 offset:22528
	ds_read_b64_tr_b16 v[232:233], v211 offset:20992
	ds_read_b64_tr_b16 v[234:235], v211 offset:23040
	ds_read_b64_tr_b16 v[236:237], v211 offset:21504
	ds_read_b64_tr_b16 v[238:239], v211 offset:23552
	ds_read_b64_tr_b16 v[240:241], v211 offset:22016
	ds_read_b64_tr_b16 v[242:243], v211 offset:24064
	s_waitcnt lgkmcnt(8)
	v_mfma_f32_32x32x16_bf16 v[48:63], v[180:183], v[220:223], v[48:63]
	s_nop 0
	v_exp_f32_e32 v112, v112
	v_exp_f32_e32 v113, v113
	v_mfma_f32_32x32x16_bf16 v[32:47], v[180:183], v[212:215], v[32:47]
	v_exp_f32_e32 v114, v114
	v_exp_f32_e32 v115, v115
	v_mfma_f32_32x32x16_bf16 v[0:15], v[180:183], v[224:227], v[0:15]
	v_exp_f32_e32 v171, v116
	v_exp_f32_e32 v220, v117
	v_mfma_f32_32x32x16_bf16 v[16:31], v[180:183], v[228:231], v[16:31]
	v_exp_f32_e32 v221, v118
	v_exp_f32_e32 v222, v119
	v_cvt_pk_bf16_f32 v180, v112, v113
	v_cvt_pk_bf16_f32 v181, v114, v115
	ds_read_b64_tr_b16 v[112:113], v211 offset:24576
	ds_read_b64_tr_b16 v[114:115], v211 offset:26624
	ds_read_b64_tr_b16 v[116:117], v211 offset:25088
	ds_read_b64_tr_b16 v[118:119], v211 offset:27136
	ds_read_b64_tr_b16 v[248:249], v211 offset:25600
	ds_read_b64_tr_b16 v[250:251], v211 offset:27648
	ds_read_b64_tr_b16 v[212:213], v211 offset:26112
	ds_read_b64_tr_b16 v[214:215], v211 offset:28160
	s_waitcnt lgkmcnt(8)
	v_mfma_f32_32x32x16_bf16 v[48:63], v[184:187], v[216:219], v[48:63]
	v_cvt_pk_bf16_f32 v182, v171, v220
	v_cvt_pk_bf16_f32 v183, v221, v222
	v_exp_f32_e32 v120, v120
	v_exp_f32_e32 v121, v121
	v_mfma_f32_32x32x16_bf16 v[32:47], v[184:187], v[232:235], v[32:47]
	v_exp_f32_e32 v122, v122
	v_exp_f32_e32 v123, v123
	v_mfma_f32_32x32x16_bf16 v[0:15], v[184:187], v[236:239], v[0:15]
	v_exp_f32_e32 v160, v124
	v_exp_f32_e32 v161, v125
	v_mfma_f32_32x32x16_bf16 v[16:31], v[184:187], v[240:243], v[16:31]
	v_exp_f32_e32 v220, v126
	v_exp_f32_e32 v221, v127
	v_cvt_pk_bf16_f32 v184, v120, v121
	v_cvt_pk_bf16_f32 v185, v122, v123
	s_waitcnt lgkmcnt(0)
	s_barrier
	v_mfma_f32_32x32x16_bf16 v[48:63], v[176:179], v[112:115], v[48:63]
	ds_read_b128 v[68:71], v76 offset:0
	ds_read_b128 v[72:75], v76 offset:8192
	ds_read_b64_tr_b16 v[120:121], v211 offset:28672
	ds_read_b64_tr_b16 v[122:123], v211 offset:30720
	ds_read_b64_tr_b16 v[124:125], v211 offset:29184
	ds_read_b64_tr_b16 v[126:127], v211 offset:31232
	ds_read_b64_tr_b16 v[252:253], v211 offset:29696
	ds_read_b64_tr_b16 v[254:255], v211 offset:31744
	ds_read_b64_tr_b16 v[216:217], v211 offset:30208
	ds_read_b64_tr_b16 v[218:219], v211 offset:32256
	v_cvt_pk_bf16_f32 v186, v160, v161
	v_cvt_pk_bf16_f32 v187, v220, v221
	v_exp_f32_e32 v96, v96
	v_exp_f32_e32 v97, v97
	v_mfma_f32_32x32x16_bf16 v[32:47], v[176:179], v[116:119], v[32:47]
	v_exp_f32_e32 v98, v98
	v_exp_f32_e32 v99, v99
	s_waitcnt vmcnt(3)
	ds_write_b128 v205, v[156:159] offset:0
	global_load_dwordx4 v[156:159], v247, s[98:99] offset:2048
	v_mfma_f32_32x32x16_bf16 v[0:15], v[176:179], v[248:251], v[0:15]
	v_exp_f32_e32 v100, v100
	v_exp_f32_e32 v101, v101
	v_mfma_f32_32x32x16_bf16 v[16:31], v[176:179], v[212:215], v[16:31]
	v_cvt_pk_bf16_f32 v176, v96, v97
	v_cvt_pk_bf16_f32 v177, v98, v99
	v_exp_f32_e32 v96, v102
	v_exp_f32_e32 v97, v103
	s_waitcnt lgkmcnt(0)
	v_mfma_f32_32x32x16_bf16 v[48:63], v[172:175], v[120:123], v[48:63]
	v_cvt_pk_bf16_f32 v178, v100, v101
	v_cvt_pk_bf16_f32 v179, v96, v97
	v_exp_f32_e32 v98, v104
	v_exp_f32_e32 v99, v105
	v_mfma_f32_32x32x16_bf16 v[32:47], v[172:175], v[124:127], v[32:47]
	v_exp_f32_e32 v96, v106
	v_exp_f32_e32 v97, v107
	s_waitcnt vmcnt(3)
	ds_write_b128 v206, v[152:155] offset:0
	global_load_dwordx4 v[152:155], v247, s[100:101] offset:2048
	v_mfma_f32_32x32x16_bf16 v[0:15], v[172:175], v[252:255], v[0:15]
	v_exp_f32_e32 v100, v108
	v_exp_f32_e32 v101, v109
	v_mfma_f32_32x32x16_bf16 v[16:31], v[172:175], v[216:219], v[16:31]
	v_cvt_pk_bf16_f32 v172, v98, v99
	v_cvt_pk_bf16_f32 v173, v96, v97
	v_exp_f32_e32 v102, v110
	v_exp_f32_e32 v103, v111
	v_cvt_pk_bf16_f32 v174, v100, v101
	v_cvt_pk_bf16_f32 v175, v102, v103
	s_add_i32 s7, s7, 1
	s_cmp_lg_u32 s55, s7
	s_cbranch_scc0 .Lunr1_x1
; #define SBAR() __builtin_amdgcn_sched_barrier(0)
; template <bool SAFE> ...
;   bf16x8 kb[8];
; #pragma unroll
;   for (int d0 = 0; d0 < 4; ++d0) { const int cb = (cb0 + d0 * 16 + hi * 8) * 2;
;     kb[2 * d0] = *reinterpret_cast<const bf16x8*>((const char*)Ks + KSWZ(r32, cb));
;     kb[2 * d0 + 1] = *reinterpret_cast<const bf16x8*>((const char*)Ks + KSWZ(32 + r32, cb)); }
;   VFrag fa, fb;
;   vfrag_issue<0>(fa, vb);
;   p0 = MFMA32(kb[0], qr[0], cinit); p1 = MFMA32(kb[1], qr[0], cinit);
; #pragma unroll
;   for (int d0 = 1; d0 < 4; ++d0) { p0 = MFMA32(kb[2 * d0], qr[d0], p0); p1 = MFMA32(kb[2 * d0 + 1], qr[d0], p1); }
;   SBAR();
;   unsigned a0, a1, b0, b1; ps = 0.f;
;   fused_ks<0, SAFE>(o, lacc, vb, fa, fb, p0, p1, ps, a0, a1, b0, b1, pa0, pa1, pa2, pa3, st, sd, dow, ones);
;   fused_ks<1, SAFE>(o, lacc, vb, fb, fa, p0, p1, ps, a0, a1, b0, b1, pa0, pa1, pa2, pa3, st, sd, dow, ones);
;   fused_ks<2, SAFE>(o, lacc, vb, fa, fb, p0, p1, ps, a0, a1, b0, b1, pa0, pa1, pa2, pa3, st, sd, dow, ones);
;   fused_ks<3, SAFE>(o, lacc, vb, fb, fa, p0, p1, ps, a0, a1, b0, b1, pa0, pa1, pa2, pa3, st, sd, dow, ones);
;   SM2_UNIT(7);
;   if constexpr (SAFE) { auto rr = __builtin_amdgcn_permlane32_swap(__float_as_uint(ps), __float_as_uint(ps), false, false);
;     ps = __uint_as_float(rr[0]) + __uint_as_float(rr[1]); }
;   SBAR();
; }
; template <bool SAFE>
; __device__ __forceinline__ void diff_core(const bf16* __restrict__ Kh, const bf16* __restrict__ Vh, const int NT, const bf16x8* qr, char* lds,
;                                           const int wid, const int lane_unused, f32x16* o, f32x16& lacc, float& l_reg) {
;     ...
;   for (int j = 1; j < NT; ++j) {
;     const bool dow = true;
;     const bf16* Kc = (const bf16*)((const char*)K_lds + bc * SHM_K);
;     StgDst sd;
;     sd.v0 = (char*)V_lds + bn * SHM_V + vst0; sd.v1 = (char*)V_lds + bn * SHM_V + vst1;
;     sd.k0 = (char*)K_lds + bn * SHM_K + kw0;  sd.k1 = (char*)K_lds + bn * SHM_K + kw1;
;     tile_step<SAFE>(o, lacc, Kc, vb0 + bp * SHM_V, qr, rk, hi, cb0, p0, p1, cinit, ps, pa0, pa1, pa2, pa3, sr_[0], sd, dow, ones);
;     SLOAD(0, min(j + 2, NT - 1) * 64);
;     SBAR();
;     if constexpr (SAFE) FIXUP(Kc, false);
;     asm volatile("s_waitcnt lgkmcnt(0)" ::: "memory"); __builtin_amdgcn_s_barrier(); asm volatile("" ::: "memory");
;     const int t_ = bp; bp = bc; bc = bn; bn = t_;
	ds_read_b128 v[212:215], v77 offset:0
	ds_read_b128 v[216:219], v77 offset:8192
	s_add_i32 s98, s7, 2
	s_min_i32 s98, s98, s64
	s_mul_i32 s98, s98, 0x60000
	s_add_u32 s98, s14, s98
	s_addc_u32 s99, s15, 0
	s_add_u32 s100, s98, 0x30000
	s_addc_u32 s101, s99, 0
	v_mfma_f32_32x32x16_bf16 v[112:127], v[68:71], v[132:135], v[80:95]
	v_mfma_f32_32x32x16_bf16 v[96:111], v[72:75], v[132:135], v[80:95]
	ds_read_b128 v[68:71], v78 offset:0
	ds_read_b128 v[72:75], v78 offset:8192
	v_mfma_f32_16x16x32_bf16 v[64:67], v[180:183], v[148:151], v[64:67]
	s_waitcnt lgkmcnt(3)
	v_mfma_f32_32x32x16_bf16 v[112:127], v[212:215], v[136:139], v[112:127]
	ds_read_b128 v[212:215], v79 offset:0
	s_waitcnt vmcnt(3)
	ds_write_b128 v188, v[166:169] offset:16384
	global_load_dwordx4 v[166:169], v247, s[98:99] offset:1024
	s_waitcnt lgkmcnt(4)
	v_mfma_f32_32x32x16_bf16 v[96:111], v[216:219], v[136:139], v[96:111]
	ds_read_b128 v[216:219], v79 offset:8192
	v_mfma_f32_16x16x32_bf16 v[64:67], v[184:187], v[148:151], v[64:67]
	s_waitcnt lgkmcnt(4)
	v_mfma_f32_32x32x16_bf16 v[112:127], v[68:71], v[140:143], v[112:127]
	ds_read_b64_tr_b16 v[220:221], v211 offset:32768
	ds_read_b64_tr_b16 v[222:223], v211 offset:34816
	s_waitcnt vmcnt(3)
	ds_write_b128 v189, v[162:165] offset:16384
	global_load_dwordx4 v[162:165], v247, s[100:101] offset:1024
	v_mfma_f32_16x16x32_bf16 v[64:67], v[176:179], v[148:151], v[64:67]
	s_waitcnt lgkmcnt(6)
	v_mfma_f32_32x32x16_bf16 v[96:111], v[72:75], v[140:143], v[96:111]
	v_mfma_f32_16x16x32_bf16 v[64:67], v[172:175], v[148:151], v[64:67]
	s_waitcnt lgkmcnt(5)
	v_mfma_f32_32x32x16_bf16 v[112:127], v[212:215], v[144:147], v[112:127]
	ds_read_b64_tr_b16 v[212:213], v211 offset:33280
	ds_read_b64_tr_b16 v[214:215], v211 offset:35328
	ds_read_b64_tr_b16 v[224:225], v211 offset:33792
	ds_read_b64_tr_b16 v[226:227], v211 offset:35840
	ds_read_b64_tr_b16 v[228:229], v211 offset:34304
	ds_read_b64_tr_b16 v[230:231], v211 offset:36352
	s_waitcnt lgkmcnt(7)
	v_mfma_f32_32x32x16_bf16 v[96:111], v[216:219], v[144:147], v[96:111]
	ds_read_b64_tr_b16 v[216:217], v211 offset:36864
	ds_read_b64_tr_b16 v[218:219], v211 offset:38912
	ds_read_b64_tr_b16 v[232:233], v211 offset:37376
	ds_read_b64_tr_b16 v[234:235], v211 offset:39424
	ds_read_b64_tr_b16 v[236:237], v211 offset:37888
	ds_read_b64_tr_b16 v[238:239], v211 offset:39936
	ds_read_b64_tr_b16 v[240:241], v211 offset:38400
	ds_read_b64_tr_b16 v[242:243], v211 offset:40448
	s_waitcnt lgkmcnt(8)
	v_mfma_f32_32x32x16_bf16 v[48:63], v[180:183], v[220:223], v[48:63]
	s_nop 0
	v_exp_f32_e32 v112, v112
	v_exp_f32_e32 v113, v113
	v_mfma_f32_32x32x16_bf16 v[32:47], v[180:183], v[212:215], v[32:47]
	v_exp_f32_e32 v114, v114
	v_exp_f32_e32 v115, v115
	v_mfma_f32_32x32x16_bf16 v[0:15], v[180:183], v[224:227], v[0:15]
	v_exp_f32_e32 v171, v116
	v_exp_f32_e32 v220, v117
	v_mfma_f32_32x32x16_bf16 v[16:31], v[180:183], v[228:231], v[16:31]
	v_exp_f32_e32 v221, v118
	v_exp_f32_e32 v222, v119
	v_cvt_pk_bf16_f32 v180, v112, v113
	v_cvt_pk_bf16_f32 v181, v114, v115
	ds_read_b64_tr_b16 v[112:113], v211 offset:40960
	ds_read_b64_tr_b16 v[114:115], v211 offset:43008
	ds_read_b64_tr_b16 v[116:117], v211 offset:41472
	ds_read_b64_tr_b16 v[118:119], v211 offset:43520
	ds_read_b64_tr_b16 v[248:249], v211 offset:41984
	ds_read_b64_tr_b16 v[250:251], v211 offset:44032
	ds_read_b64_tr_b16 v[212:213], v211 offset:42496
	ds_read_b64_tr_b16 v[214:215], v211 offset:44544
	s_waitcnt lgkmcnt(8)
	v_mfma_f32_32x32x16_bf16 v[48:63], v[184:187], v[216:219], v[48:63]
	v_cvt_pk_bf16_f32 v182, v171, v220
	v_cvt_pk_bf16_f32 v183, v221, v222
	v_exp_f32_e32 v120, v120
	v_exp_f32_e32 v121, v121
	v_mfma_f32_32x32x16_bf16 v[32:47], v[184:187], v[232:235], v[32:47]
	v_exp_f32_e32 v122, v122
	v_exp_f32_e32 v123, v123
	v_mfma_f32_32x32x16_bf16 v[0:15], v[184:187], v[236:239], v[0:15]
	v_exp_f32_e32 v160, v124
	v_exp_f32_e32 v161, v125
	v_mfma_f32_32x32x16_bf16 v[16:31], v[184:187], v[240:243], v[16:31]
	v_exp_f32_e32 v220, v126
	v_exp_f32_e32 v221, v127
	v_cvt_pk_bf16_f32 v184, v120, v121
	v_cvt_pk_bf16_f32 v185, v122, v123
	s_waitcnt lgkmcnt(0)
	s_barrier
	v_mfma_f32_32x32x16_bf16 v[48:63], v[176:179], v[112:115], v[48:63]
	ds_read_b128 v[68:71], v76 offset:16384
	ds_read_b128 v[72:75], v76 offset:24576
	ds_read_b64_tr_b16 v[120:121], v211 offset:45056
	ds_read_b64_tr_b16 v[122:123], v211 offset:47104
	ds_read_b64_tr_b16 v[124:125], v211 offset:45568
	ds_read_b64_tr_b16 v[126:127], v211 offset:47616
	ds_read_b64_tr_b16 v[252:253], v211 offset:46080
	ds_read_b64_tr_b16 v[254:255], v211 offset:48128
	ds_read_b64_tr_b16 v[216:217], v211 offset:46592
	ds_read_b64_tr_b16 v[218:219], v211 offset:48640
	v_cvt_pk_bf16_f32 v186, v160, v161
	v_cvt_pk_bf16_f32 v187, v220, v221
	v_exp_f32_e32 v96, v96
	v_exp_f32_e32 v97, v97
	v_mfma_f32_32x32x16_bf16 v[32:47], v[176:179], v[116:119], v[32:47]
	v_exp_f32_e32 v98, v98
	v_exp_f32_e32 v99, v99
	s_waitcnt vmcnt(3)
	ds_write_b128 v205, v[156:159] offset:16384
	global_load_dwordx4 v[156:159], v247, s[98:99] offset:2048
	v_mfma_f32_32x32x16_bf16 v[0:15], v[176:179], v[248:251], v[0:15]
	v_exp_f32_e32 v100, v100
	v_exp_f32_e32 v101, v101
	v_mfma_f32_32x32x16_bf16 v[16:31], v[176:179], v[212:215], v[16:31]
	v_cvt_pk_bf16_f32 v176, v96, v97
	v_cvt_pk_bf16_f32 v177, v98, v99
	v_exp_f32_e32 v96, v102
	v_exp_f32_e32 v97, v103
	s_waitcnt lgkmcnt(0)
	v_mfma_f32_32x32x16_bf16 v[48:63], v[172:175], v[120:123], v[48:63]
	v_cvt_pk_bf16_f32 v178, v100, v101
	v_cvt_pk_bf16_f32 v179, v96, v97
	v_exp_f32_e32 v98, v104
	v_exp_f32_e32 v99, v105
	v_mfma_f32_32x32x16_bf16 v[32:47], v[172:175], v[124:127], v[32:47]
	v_exp_f32_e32 v96, v106
	v_exp_f32_e32 v97, v107
	s_waitcnt vmcnt(3)
	ds_write_b128 v206, v[152:155] offset:16384
	global_load_dwordx4 v[152:155], v247, s[100:101] offset:2048
	v_mfma_f32_32x32x16_bf16 v[0:15], v[172:175], v[252:255], v[0:15]
	v_exp_f32_e32 v100, v108
	v_exp_f32_e32 v101, v109
	v_mfma_f32_32x32x16_bf16 v[16:31], v[172:175], v[216:219], v[16:31]
	v_cvt_pk_bf16_f32 v172, v98, v99
	v_cvt_pk_bf16_f32 v173, v96, v97
	v_exp_f32_e32 v102, v110
	v_exp_f32_e32 v103, v111
	v_cvt_pk_bf16_f32 v174, v100, v101
	v_cvt_pk_bf16_f32 v175, v102, v103
	s_add_i32 s7, s7, 1
	s_cmp_lg_u32 s55, s7
	s_cbranch_scc1 .LBB0_316
	s_mov_b32 s11, 0
	s_branch .Lunr1_join
; #define MFMA32(a, b, c) __builtin_amdgcn_mfma_f32_32x32x16_bf16(a, b, c, 0, 0, 0)
; template <bool SAFE>
; __device__ __forceinline__ void diff_core(const bf16* __restrict__ Kh, const bf16* __restrict__ Vh, const int NT, const bf16x8* qr, char* lds,
;                                           const int wid, const int lane_unused, f32x16* o, f32x16& lacc, float& l_reg) {
;     ...
;   pv_d0(o, vb0 + bp * SHM_V, pa0, pa1, pa2, pa3);
;   if constexpr (!SAFE) {
;     lacc = MFMA32(pa0, ones, lacc); lacc = MFMA32(pa1, ones, lacc); lacc = MFMA32(pa2, ones, lacc); lacc = MFMA32(pa3, ones, lacc); }
; __device__ __forceinline__ void diff_attn_item(const bf16* __restrict__ qkv, bf16* __restrict__ mix, const float* __restrict__ dg,
;                                int tok0  , int key0  , int seq, int head, float lam, float oscale, const int W) {
;     ...
;     bool bad = (FORCE_SAFE != 0);
; #pragma unroll
;     for (int r = 0; r < 16; ++r) bad = bad || !(lacc[r] < 1.0e30f);
;     if (lane == 0) flag_l[wid] = __any(bad) ? 1 : 0;
.Lunr1_x0:
	s_movk_i32 s11, 0x4000
	s_branch .Lunr1_join
.Lunr1_x1:
	s_mov_b32 s11, 0x8000
.Lunr1_join:
	v_mov_b32_e32 v160, v180
	v_mov_b32_e32 v161, v181
	v_mov_b32_e32 v170, v184
	v_mov_b32_e32 v171, v185
	v_mov_b32_e32 v180, v176
	v_mov_b32_e32 v181, v177
	v_mov_b32_e32 v188, v172
	v_mov_b32_e32 v189, v173
	s_waitcnt vmcnt(0)
	v_add_u32_e32 v168, s11, v211
	ds_read_b64_tr_b16 v[80:81], v168 offset:0
	ds_read_b64_tr_b16 v[82:83], v168 offset:0x800
	ds_read_b64_tr_b16 v[84:85], v168 offset:0x1000
	ds_read_b64_tr_b16 v[86:87], v168 offset:0x1800
	ds_read_b64_tr_b16 v[88:89], v168 offset:0x2000
	ds_read_b64_tr_b16 v[90:91], v168 offset:0x2800
	ds_read_b64_tr_b16 v[92:93], v168 offset:0x3000
	ds_read_b64_tr_b16 v[94:95], v168 offset:0x3800
	s_waitcnt lgkmcnt(0)
	s_waitcnt vmcnt(0)
	v_mov_b32_e32 v162, v182
	v_mov_b32_e32 v163, v183
	v_mov_b32_e32 v172, v186
	v_mov_b32_e32 v173, v187
	v_mov_b32_e32 v182, v178
	v_mov_b32_e32 v183, v179
	v_mov_b32_e32 v190, v174
	v_mov_b32_e32 v191, v175
	ds_read_b64_tr_b16 v[96:97], v168 offset:0x200
	ds_read_b64_tr_b16 v[98:99], v168 offset:0xa00
	ds_read_b64_tr_b16 v[100:101], v168 offset:0x1200
	ds_read_b64_tr_b16 v[102:103], v168 offset:0x1a00
	ds_read_b64_tr_b16 v[104:105], v168 offset:0x2200
	ds_read_b64_tr_b16 v[106:107], v168 offset:0x2a00
	ds_read_b64_tr_b16 v[108:109], v168 offset:0x3200
	ds_read_b64_tr_b16 v[110:111], v168 offset:0x3a00
	s_waitcnt lgkmcnt(0)
	ds_read_b64_tr_b16 v[112:113], v168 offset:0x400
	ds_read_b64_tr_b16 v[114:115], v168 offset:0xc00
	ds_read_b64_tr_b16 v[116:117], v168 offset:0x1400
	ds_read_b64_tr_b16 v[118:119], v168 offset:0x1c00
	ds_read_b64_tr_b16 v[120:121], v168 offset:0x2400
	ds_read_b64_tr_b16 v[122:123], v168 offset:0x2c00
	ds_read_b64_tr_b16 v[124:125], v168 offset:0x3400
	ds_read_b64_tr_b16 v[126:127], v168 offset:0x3c00
	s_waitcnt lgkmcnt(0)
	ds_read_b64_tr_b16 v[152:153], v168 offset:0x600
	ds_read_b64_tr_b16 v[154:155], v168 offset:0xe00
	ds_read_b64_tr_b16 v[156:157], v168 offset:0x1600
	ds_read_b64_tr_b16 v[158:159], v168 offset:0x1e00
	ds_read_b64_tr_b16 v[164:165], v168 offset:0x2600
	ds_read_b64_tr_b16 v[166:167], v168 offset:0x2e00
	ds_read_b64_tr_b16 v[174:175], v168 offset:0x3600
	ds_read_b64_tr_b16 v[176:177], v168 offset:0x3e00
	s_waitcnt lgkmcnt(0)
	v_mfma_f32_16x16x32_bf16 v[64:67], v[160:163], v[148:151], v[64:67]
	v_cmp_eq_u32_e32 vcc, 0, v200
	v_mfma_f32_32x32x16_bf16 v[48:63], v[160:163], v[80:83], v[48:63]
	v_mfma_f32_32x32x16_bf16 v[32:47], v[160:163], v[96:99], v[32:47]
	v_mfma_f32_32x32x16_bf16 v[0:15], v[160:163], v[112:115], v[0:15]
	v_mfma_f32_32x32x16_bf16 v[16:31], v[160:163], v[152:155], v[16:31]
	v_mfma_f32_16x16x32_bf16 v[64:67], v[170:173], v[148:151], v[64:67]
	v_mfma_f32_32x32x16_bf16 v[48:63], v[170:173], v[84:87], v[48:63]
	v_mfma_f32_32x32x16_bf16 v[32:47], v[170:173], v[100:103], v[32:47]
	v_mfma_f32_32x32x16_bf16 v[0:15], v[170:173], v[116:119], v[0:15]
	v_mfma_f32_32x32x16_bf16 v[16:31], v[170:173], v[156:159], v[16:31]
	v_mfma_f32_16x16x32_bf16 v[64:67], v[180:183], v[148:151], v[64:67]
	v_mfma_f32_32x32x16_bf16 v[48:63], v[180:183], v[88:91], v[48:63]
	v_mfma_f32_32x32x16_bf16 v[32:47], v[180:183], v[104:107], v[32:47]
	v_mfma_f32_32x32x16_bf16 v[0:15], v[180:183], v[120:123], v[0:15]
	v_mfma_f32_32x32x16_bf16 v[16:31], v[180:183], v[164:167], v[16:31]
	v_mfma_f32_16x16x32_bf16 v[64:67], v[188:191], v[148:151], v[64:67]
	v_mfma_f32_32x32x16_bf16 v[48:63], v[188:191], v[92:95], v[48:63]
	v_mfma_f32_32x32x16_bf16 v[32:47], v[188:191], v[108:111], v[32:47]
	v_mfma_f32_32x32x16_bf16 v[0:15], v[188:191], v[124:127], v[0:15]
	v_mfma_f32_32x32x16_bf16 v[16:31], v[188:191], v[174:177], v[16:31]
	v_and_b32_e32 v248, 15, v200
	v_lshrrev_b32_e32 v249, 4, v200
	v_and_b32_e32 v250, 1, v200
	v_lshlrev_b32_e32 v249, 4, v249
	v_lshl_add_u32 v249, v250, 6, v249
	v_add_u32_e32 v249, s62, v249
	v_cmp_gt_u32_e64 s[98:99], 2, v248
	v_lshl_add_u32 v250, v198, 4, s62
	s_nop 7
	s_and_saveexec_b64 s[100:101], s[98:99]
	ds_write_b128 v249, v[64:67]
	s_mov_b64 exec, s[100:101]
	s_waitcnt lgkmcnt(0)
	ds_read_b128 v[64:67], v250
	ds_read_b128 v[68:71], v250 offset:32
	ds_read_b128 v[72:75], v250 offset:64
	ds_read_b128 v[76:79], v250 offset:96
	s_waitcnt lgkmcnt(0)
	s_and_saveexec_b64 s[10:11], vcc
	s_cbranch_execz .LBB0_319
	s_nop 5
	v_cmp_ngt_f32_e32 vcc, s44, v64
	v_cmp_ngt_f32_e64 s[6:7], s44, v65
	s_or_b64 s[6:7], vcc, s[6:7]
	v_cmp_ngt_f32_e32 vcc, s44, v66
	s_or_b64 s[6:7], s[6:7], vcc
	v_cmp_ngt_f32_e32 vcc, s44, v67
	s_or_b64 s[6:7], s[6:7], vcc
	v_cmp_ngt_f32_e32 vcc, s44, v68
	s_or_b64 s[6:7], s[6:7], vcc
	v_cmp_ngt_f32_e32 vcc, s44, v69
	s_or_b64 s[6:7], s[6:7], vcc
	v_cmp_ngt_f32_e32 vcc, s44, v70
	s_or_b64 s[6:7], s[6:7], vcc
	v_cmp_ngt_f32_e32 vcc, s44, v71
	s_or_b64 s[6:7], s[6:7], vcc
	v_cmp_ngt_f32_e32 vcc, s44, v72
	s_or_b64 s[6:7], s[6:7], vcc
	v_cmp_ngt_f32_e32 vcc, s44, v73
	s_or_b64 s[6:7], s[6:7], vcc
	v_cmp_ngt_f32_e32 vcc, s44, v74
	s_or_b64 s[6:7], s[6:7], vcc
	v_cmp_ngt_f32_e32 vcc, s44, v75
	s_or_b64 s[6:7], s[6:7], vcc
	v_cmp_ngt_f32_e32 vcc, s44, v76
	s_or_b64 s[6:7], s[6:7], vcc
	v_cmp_ngt_f32_e32 vcc, s44, v77
	s_or_b64 s[6:7], s[6:7], vcc
	v_cmp_ngt_f32_e32 vcc, s44, v78
	s_or_b64 s[6:7], s[6:7], vcc
	v_cmp_ngt_f32_e32 vcc, s44, v79
	s_or_b64 s[6:7], s[6:7], vcc
	v_cndmask_b32_e64 v80, 0, 1, s[6:7]
	v_cmp_ne_u32_e32 vcc, 0, v80
	s_cmp_lg_u64 vcc, 0
	s_cselect_b64 s[6:7], -1, 0
	v_cndmask_b32_e64 v80, 0, 1, s[6:7]
	v_readlane_b32 s6, v246, 17
	s_nop 1
	v_mov_b32_e32 v81, s6
	ds_write_b32 v81, v80
